# write-through (sc1) stores also in EpiResid (out, down) and EpiGate1
# baseline (speedup 1.0000x reference)
.LBB0_591:
	s_lshl_b32 s0, s71, 8
	v_mbcnt_lo_u32_b32 v96, -1, 0
	v_mbcnt_hi_u32_b32 v96, -1, v96
	s_add_i32 s0, s0, s66
	v_and_or_b32 v166, v96, 15, s0
	s_lshl_b32 s0, s70, 8
	v_ashrrev_i32_e32 v96, 1, v96
	s_or_b32 s0, s0, s67
	v_and_b32_e32 v96, -8, v96
	v_add_u32_e32 v96, s0, v96
	v_ashrrev_i32_e32 v97, 31, v96
	v_mov_b64_e32 v[170:171], s[36:37]
	v_ashrrev_i32_e32 v167, 31, v166
	v_mad_i64_i32 v[98:99], s[0:1], v166, s15, v[170:171]
	v_lshlrev_b64 v[168:169], 1, v[96:97]
	v_lshlrev_b64 v[108:109], 11, v[166:167]
	v_lshl_add_u64 v[96:97], v[98:99], 0, v[168:169]
	v_lshl_add_u64 v[108:109], s[30:31], 0, v[108:109]
	v_add_co_u32_e32 v98, vcc, s11, v96
	v_lshl_add_u64 v[182:183], v[108:109], 0, v[168:169]
	s_nop 0
	v_addc_co_u32_e32 v99, vcc, 0, v97, vcc
	global_load_dwordx4 v[178:181], v[182:183], off
	global_load_dwordx4 v[186:189], v[98:99], off
	v_lshl_add_u64 v[96:97], v[96:97], 0, s[34:35]
	global_load_dwordx4 v[194:197], v[96:97], off offset:256
	v_or_b32_e32 v96, 16, v166
	v_ashrrev_i32_e32 v97, 31, v96
	global_load_dwordx4 v[198:201], v[182:183], off offset:256
	v_mad_i64_i32 v[110:111], s[0:1], v96, s15, v[170:171]
	v_lshlrev_b64 v[96:97], 11, v[96:97]
	v_lshl_add_u64 v[110:111], v[110:111], 0, v[168:169]
	v_lshl_add_u64 v[96:97], s[30:31], 0, v[96:97]
	v_add_co_u32_e32 v124, vcc, s11, v110
	v_lshl_add_u64 v[190:191], v[96:97], 0, v[168:169]
	s_nop 0
	v_addc_co_u32_e32 v125, vcc, 0, v111, vcc
	global_load_dwordx4 v[202:205], v[124:125], off
	global_load_dwordx4 v[206:209], v[190:191], off
	v_or_b32_e32 v98, 32, v166
	v_mad_i64_i32 v[120:121], s[0:1], v98, s15, v[170:171]
	v_or_b32_e32 v108, 48, v166
	v_ashrrev_i32_e32 v99, 31, v98
	v_lshl_add_u64 v[120:121], v[120:121], 0, v[168:169]
	v_mad_i64_i32 v[122:123], s[0:1], v108, s15, v[170:171]
	v_lshlrev_b64 v[98:99], 11, v[98:99]
	v_lshl_add_u64 v[96:97], v[120:121], 0, s[34:35]
	v_add_co_u32_e32 v120, vcc, s11, v120
	v_ashrrev_i32_e32 v109, 31, v108
	v_lshl_add_u64 v[98:99], s[30:31], 0, v[98:99]
	v_lshl_add_u64 v[122:123], v[122:123], 0, v[168:169]
	v_addc_co_u32_e32 v121, vcc, 0, v121, vcc
	v_lshlrev_b64 v[108:109], 11, v[108:109]
	v_lshl_add_u64 v[174:175], v[98:99], 0, v[168:169]
	v_lshl_add_u64 v[98:99], v[122:123], 0, s[34:35]
	v_add_co_u32_e32 v122, vcc, s11, v122
	v_lshl_add_u64 v[108:109], s[30:31], 0, v[108:109]
	v_lshl_add_u64 v[110:111], v[110:111], 0, s[34:35]
	v_addc_co_u32_e32 v123, vcc, 0, v123, vcc
	v_lshl_add_u64 v[172:173], v[108:109], 0, v[168:169]
	global_load_dwordx4 v[210:213], v[110:111], off offset:256
	global_load_dwordx4 v[214:217], v[190:191], off offset:256
	global_load_dwordx4 v[156:159], v[120:121], off
	global_load_dwordx4 v[136:139], v[96:97], off offset:256
	global_load_dwordx4 v[152:155], v[174:175], off
	global_load_dwordx4 v[128:131], v[174:175], off offset:256
	global_load_dwordx4 v[124:127], v[122:123], off
	global_load_dwordx4 v[108:111], v[98:99], off offset:256
	s_nop 0
	global_load_dwordx4 v[120:123], v[172:173], off
	global_load_dwordx4 v[96:99], v[172:173], off offset:256
	v_mov_b64_e32 v[242:243], v[184:185]
	v_mov_b64_e32 v[184:185], 0xff
	s_waitcnt vmcnt(0)
	v_lshlrev_b32_e32 v218, 16, v178
	v_and_b32_e32 v219, 0xffff0000, v178
	v_lshlrev_b32_e32 v220, 16, v186
	v_and_b32_e32 v221, 0xffff0000, v186
	v_lshlrev_b32_e32 v186, 16, v187
	v_and_b32_e32 v187, 0xffff0000, v187
	v_lshlrev_b32_e32 v178, 16, v179
	v_and_b32_e32 v179, 0xffff0000, v179
	v_lshlrev_b32_e32 v222, 16, v188
	v_and_b32_e32 v223, 0xffff0000, v188
	v_lshlrev_b32_e32 v188, 16, v189
	v_and_b32_e32 v189, 0xffff0000, v189
	v_pk_fma_f32 v[150:151], v[150:151], v[186:187], v[178:179]
	v_lshlrev_b32_e32 v178, 16, v180
	v_and_b32_e32 v179, 0xffff0000, v180
	v_lshlrev_b32_e32 v180, 16, v181
	v_and_b32_e32 v181, 0xffff0000, v181
	v_pk_fma_f32 v[180:181], v[146:147], v[188:189], v[180:181]
	v_pk_fma_f32 v[146:147], v[144:145], v[222:223], v[178:179]
	v_pk_fma_f32 v[148:149], v[148:149], v[220:221], v[218:219]
	v_lshlrev_b32_e32 v178, 16, v198
	v_cvt_pk_bf16_f32 v144, v148, v149
	v_cvt_pk_bf16_f32 v145, v150, v151
	v_cvt_pk_bf16_f32 v146, v146, v147
	v_cvt_pk_bf16_f32 v147, v180, v181
	global_store_dwordx4 v[182:183], v[144:147], off sc1
	v_and_b32_e32 v179, 0xffff0000, v198
	v_lshlrev_b32_e32 v180, 16, v199
	v_lshlrev_b32_e32 v144, 16, v194
	v_and_b32_e32 v145, 0xffff0000, v194
	v_lshlrev_b32_e32 v146, 16, v195
	v_and_b32_e32 v147, 0xffff0000, v195
	v_and_b32_e32 v181, 0xffff0000, v199
	v_lshlrev_b32_e32 v148, 16, v196
	v_and_b32_e32 v149, 0xffff0000, v196
	v_lshlrev_b32_e32 v150, 16, v197
	v_and_b32_e32 v151, 0xffff0000, v197
	v_pk_fma_f32 v[142:143], v[142:143], v[146:147], v[180:181]
	v_pk_fma_f32 v[140:141], v[140:141], v[144:145], v[178:179]
	v_lshlrev_b32_e32 v144, 16, v200
	v_and_b32_e32 v145, 0xffff0000, v200
	v_lshlrev_b32_e32 v146, 16, v201
	v_and_b32_e32 v147, 0xffff0000, v201
	v_pk_fma_f32 v[146:147], v[134:135], v[150:151], v[146:147]
	v_pk_fma_f32 v[134:135], v[132:133], v[148:149], v[144:145]
	v_cvt_pk_bf16_f32 v132, v140, v141
	v_cvt_pk_bf16_f32 v133, v142, v143
	v_lshlrev_b32_e32 v144, 16, v206
	v_cvt_pk_bf16_f32 v134, v134, v135
	v_cvt_pk_bf16_f32 v135, v146, v147
	global_store_dwordx4 v[182:183], v[132:135], off offset:256 sc1
	v_and_b32_e32 v145, 0xffff0000, v206
	v_lshlrev_b32_e32 v146, 16, v207
	v_lshlrev_b32_e32 v132, 16, v202
	v_and_b32_e32 v133, 0xffff0000, v202
	v_lshlrev_b32_e32 v134, 16, v203
	v_and_b32_e32 v135, 0xffff0000, v203
	v_and_b32_e32 v147, 0xffff0000, v207
	v_lshlrev_b32_e32 v140, 16, v204
	v_and_b32_e32 v141, 0xffff0000, v204
	v_lshlrev_b32_e32 v142, 16, v205
	v_and_b32_e32 v143, 0xffff0000, v205
	v_pk_fma_f32 v[118:119], v[118:119], v[134:135], v[146:147]
	v_pk_fma_f32 v[116:117], v[116:117], v[132:133], v[144:145]
	v_lshlrev_b32_e32 v132, 16, v208
	v_and_b32_e32 v133, 0xffff0000, v208
	v_lshlrev_b32_e32 v134, 16, v209
	v_and_b32_e32 v135, 0xffff0000, v209
	v_pk_fma_f32 v[134:135], v[114:115], v[142:143], v[134:135]
	v_pk_fma_f32 v[114:115], v[112:113], v[140:141], v[132:133]
	v_cvt_pk_bf16_f32 v112, v116, v117
	v_cvt_pk_bf16_f32 v113, v118, v119
	v_lshlrev_b32_e32 v132, 16, v214
	v_cvt_pk_bf16_f32 v114, v114, v115
	v_cvt_pk_bf16_f32 v115, v134, v135
	global_store_dwordx4 v[190:191], v[112:115], off sc1
	v_and_b32_e32 v133, 0xffff0000, v214
	v_lshlrev_b32_e32 v134, 16, v215
	v_lshlrev_b32_e32 v112, 16, v210
	v_and_b32_e32 v113, 0xffff0000, v210
	v_lshlrev_b32_e32 v114, 16, v211
	v_and_b32_e32 v115, 0xffff0000, v211
	v_and_b32_e32 v135, 0xffff0000, v215
	v_lshlrev_b32_e32 v116, 16, v212
	v_and_b32_e32 v117, 0xffff0000, v212
	v_lshlrev_b32_e32 v118, 16, v213
	v_and_b32_e32 v119, 0xffff0000, v213
	v_pk_fma_f32 v[106:107], v[106:107], v[114:115], v[134:135]
	v_pk_fma_f32 v[104:105], v[104:105], v[112:113], v[132:133]
	v_lshlrev_b32_e32 v112, 16, v216
	v_and_b32_e32 v113, 0xffff0000, v216
	v_lshlrev_b32_e32 v114, 16, v217
	v_and_b32_e32 v115, 0xffff0000, v217
	v_pk_fma_f32 v[114:115], v[102:103], v[118:119], v[114:115]
	v_pk_fma_f32 v[102:103], v[100:101], v[116:117], v[112:113]
	v_cvt_pk_bf16_f32 v100, v104, v105
	v_cvt_pk_bf16_f32 v101, v106, v107
	v_lshlrev_b32_e32 v112, 16, v152
	v_cvt_pk_bf16_f32 v102, v102, v103
	v_cvt_pk_bf16_f32 v103, v114, v115
	global_store_dwordx4 v[190:191], v[100:103], off offset:256 sc1
	v_and_b32_e32 v113, 0xffff0000, v152
	v_lshlrev_b32_e32 v114, 16, v153
	v_lshlrev_b32_e32 v100, 16, v156
	v_and_b32_e32 v101, 0xffff0000, v156
	v_lshlrev_b32_e32 v102, 16, v157
	v_and_b32_e32 v103, 0xffff0000, v157
	v_and_b32_e32 v115, 0xffff0000, v153
	v_lshlrev_b32_e32 v104, 16, v158
	v_and_b32_e32 v105, 0xffff0000, v158
	v_lshlrev_b32_e32 v106, 16, v159
	v_and_b32_e32 v107, 0xffff0000, v159
	v_pk_fma_f32 v[94:95], v[94:95], v[102:103], v[114:115]
	v_pk_fma_f32 v[92:93], v[92:93], v[100:101], v[112:113]
	v_lshlrev_b32_e32 v100, 16, v154
	v_and_b32_e32 v101, 0xffff0000, v154
	v_lshlrev_b32_e32 v102, 16, v155
	v_and_b32_e32 v103, 0xffff0000, v155
	v_pk_fma_f32 v[102:103], v[90:91], v[106:107], v[102:103]
	v_pk_fma_f32 v[90:91], v[88:89], v[104:105], v[100:101]
	v_cvt_pk_bf16_f32 v88, v92, v93
	v_cvt_pk_bf16_f32 v89, v94, v95
	v_lshlrev_b32_e32 v100, 16, v128
	v_cvt_pk_bf16_f32 v90, v90, v91
	v_cvt_pk_bf16_f32 v91, v102, v103
	global_store_dwordx4 v[174:175], v[88:91], off sc1
	v_and_b32_e32 v101, 0xffff0000, v128
	v_lshlrev_b32_e32 v102, 16, v129
	v_lshlrev_b32_e32 v88, 16, v136
	v_and_b32_e32 v89, 0xffff0000, v136
	v_lshlrev_b32_e32 v90, 16, v137
	v_and_b32_e32 v91, 0xffff0000, v137
	v_and_b32_e32 v103, 0xffff0000, v129
	v_lshlrev_b32_e32 v92, 16, v138
	v_and_b32_e32 v93, 0xffff0000, v138
	v_lshlrev_b32_e32 v94, 16, v139
	v_and_b32_e32 v95, 0xffff0000, v139
	v_pk_fma_f32 v[86:87], v[86:87], v[90:91], v[102:103]
	v_pk_fma_f32 v[84:85], v[84:85], v[88:89], v[100:101]
	v_lshlrev_b32_e32 v88, 16, v130
	v_and_b32_e32 v89, 0xffff0000, v130
	v_lshlrev_b32_e32 v90, 16, v131
	v_and_b32_e32 v91, 0xffff0000, v131
	v_pk_fma_f32 v[90:91], v[82:83], v[94:95], v[90:91]
	v_pk_fma_f32 v[82:83], v[80:81], v[92:93], v[88:89]
	v_cvt_pk_bf16_f32 v80, v84, v85
	v_cvt_pk_bf16_f32 v81, v86, v87
	v_lshlrev_b32_e32 v88, 16, v120
	v_cvt_pk_bf16_f32 v82, v82, v83
	v_cvt_pk_bf16_f32 v83, v90, v91
	global_store_dwordx4 v[174:175], v[80:83], off offset:256 sc1
	v_and_b32_e32 v89, 0xffff0000, v120
	v_lshlrev_b32_e32 v90, 16, v121
	v_lshlrev_b32_e32 v80, 16, v124
	v_and_b32_e32 v81, 0xffff0000, v124
	v_lshlrev_b32_e32 v82, 16, v125
	v_and_b32_e32 v83, 0xffff0000, v125
	v_and_b32_e32 v91, 0xffff0000, v121
	v_lshlrev_b32_e32 v84, 16, v126
	v_and_b32_e32 v85, 0xffff0000, v126
	v_lshlrev_b32_e32 v86, 16, v127
	v_and_b32_e32 v87, 0xffff0000, v127
	v_pk_fma_f32 v[78:79], v[78:79], v[82:83], v[90:91]
	v_pk_fma_f32 v[76:77], v[76:77], v[80:81], v[88:89]
	v_lshlrev_b32_e32 v80, 16, v122
	v_and_b32_e32 v81, 0xffff0000, v122
	v_lshlrev_b32_e32 v82, 16, v123
	v_and_b32_e32 v83, 0xffff0000, v123
	v_pk_fma_f32 v[82:83], v[74:75], v[86:87], v[82:83]
	v_pk_fma_f32 v[74:75], v[72:73], v[84:85], v[80:81]
	v_cvt_pk_bf16_f32 v72, v76, v77
	v_cvt_pk_bf16_f32 v73, v78, v79
	v_lshlrev_b32_e32 v80, 16, v96
	v_cvt_pk_bf16_f32 v74, v74, v75
	v_cvt_pk_bf16_f32 v75, v82, v83
	global_store_dwordx4 v[172:173], v[72:75], off sc1
	v_and_b32_e32 v81, 0xffff0000, v96
	v_lshlrev_b32_e32 v82, 16, v97
	v_lshlrev_b32_e32 v72, 16, v108
	v_and_b32_e32 v73, 0xffff0000, v108
	v_lshlrev_b32_e32 v74, 16, v109
	v_and_b32_e32 v75, 0xffff0000, v109
	v_and_b32_e32 v83, 0xffff0000, v97
	v_lshlrev_b32_e32 v76, 16, v110
	v_and_b32_e32 v77, 0xffff0000, v110
	v_lshlrev_b32_e32 v78, 16, v111
	v_and_b32_e32 v79, 0xffff0000, v111
	v_pk_fma_f32 v[70:71], v[70:71], v[74:75], v[82:83]
	v_pk_fma_f32 v[68:69], v[68:69], v[72:73], v[80:81]
	v_lshlrev_b32_e32 v72, 16, v98
	v_and_b32_e32 v73, 0xffff0000, v98
	v_lshlrev_b32_e32 v74, 16, v99
	v_and_b32_e32 v75, 0xffff0000, v99
	v_pk_fma_f32 v[74:75], v[66:67], v[78:79], v[74:75]
	v_pk_fma_f32 v[66:67], v[64:65], v[76:77], v[72:73]
	v_cvt_pk_bf16_f32 v64, v68, v69
	v_add_u32_e32 v68, 0x80, v166
	v_cvt_pk_bf16_f32 v65, v70, v71
	v_mad_i64_i32 v[70:71], s[0:1], v68, s15, v[170:171]
	v_ashrrev_i32_e32 v69, 31, v68
	v_lshl_add_u64 v[70:71], v[70:71], 0, v[168:169]
	v_lshlrev_b64 v[68:69], 11, v[68:69]
	v_add_co_u32_e32 v72, vcc, s11, v70
	v_lshl_add_u64 v[68:69], s[30:31], 0, v[68:69]
	s_nop 0
	v_addc_co_u32_e32 v73, vcc, 0, v71, vcc
	v_lshl_add_u64 v[134:135], v[68:69], 0, v[168:169]
	v_cvt_pk_bf16_f32 v66, v66, v67
	v_cvt_pk_bf16_f32 v67, v74, v75
	global_load_dwordx4 v[102:105], v[72:73], off
	global_load_dwordx4 v[106:109], v[134:135], off
	s_waitcnt vmcnt(1)
	v_lshlrev_b32_e32 v136, 16, v102
	global_store_dwordx4 v[172:173], v[64:67], off offset:256 sc1
	v_and_b32_e32 v137, 0xffff0000, v102
	v_lshlrev_b32_e32 v102, 16, v103
	v_lshl_add_u64 v[64:65], v[70:71], 0, s[34:35]
	global_load_dwordx4 v[110:113], v[64:65], off offset:256
	global_load_dwordx4 v[114:117], v[134:135], off offset:256
	v_add_u32_e32 v64, 0x90, v166
	v_mad_i64_i32 v[66:67], s[0:1], v64, s15, v[170:171]
	v_ashrrev_i32_e32 v65, 31, v64
	v_lshl_add_u64 v[66:67], v[66:67], 0, v[168:169]
	v_lshlrev_b64 v[64:65], 11, v[64:65]
	v_lshl_add_u64 v[68:69], v[66:67], 0, s[34:35]
	v_add_co_u32_e32 v66, vcc, s11, v66
	v_lshl_add_u64 v[64:65], s[30:31], 0, v[64:65]
	s_nop 0
	v_addc_co_u32_e32 v67, vcc, 0, v67, vcc
	v_lshl_add_u64 v[100:101], v[64:65], 0, v[168:169]
	global_load_dwordx4 v[118:121], v[66:67], off
	global_load_dwordx4 v[122:125], v[68:69], off offset:256
	global_load_dwordx4 v[126:129], v[100:101], off
	global_load_dwordx4 v[130:133], v[100:101], off offset:256
	v_add_u32_e32 v64, 0xa0, v166
	v_mad_i64_i32 v[66:67], s[0:1], v64, s15, v[170:171]
	v_ashrrev_i32_e32 v65, 31, v64
	v_lshl_add_u64 v[66:67], v[66:67], 0, v[168:169]
	v_lshlrev_b64 v[64:65], 11, v[64:65]
	v_lshl_add_u64 v[68:69], v[66:67], 0, s[34:35]
	v_add_co_u32_e32 v66, vcc, s11, v66
	v_lshl_add_u64 v[64:65], s[30:31], 0, v[64:65]
	s_nop 0
	v_addc_co_u32_e32 v67, vcc, 0, v67, vcc
	v_lshl_add_u64 v[98:99], v[64:65], 0, v[168:169]
	global_load_dwordx4 v[92:95], v[66:67], off
	global_load_dwordx4 v[84:87], v[68:69], off offset:256
	global_load_dwordx4 v[88:91], v[98:99], off
	global_load_dwordx4 v[80:83], v[98:99], off offset:256
	v_add_u32_e32 v64, 0xb0, v166
	v_mad_i64_i32 v[66:67], s[0:1], v64, s15, v[170:171]
	v_ashrrev_i32_e32 v65, 31, v64
	v_lshl_add_u64 v[66:67], v[66:67], 0, v[168:169]
	v_lshlrev_b64 v[64:65], 11, v[64:65]
	v_lshl_add_u64 v[68:69], v[66:67], 0, s[34:35]
	v_add_co_u32_e32 v66, vcc, s11, v66
	v_lshl_add_u64 v[64:65], s[30:31], 0, v[64:65]
	s_nop 0
	v_addc_co_u32_e32 v67, vcc, 0, v67, vcc
	v_lshl_add_u64 v[96:97], v[64:65], 0, v[168:169]
	global_load_dwordx4 v[76:79], v[66:67], off
	s_nop 0
	global_load_dwordx4 v[68:71], v[68:69], off offset:256
	s_nop 0
	global_load_dwordx4 v[72:75], v[96:97], off
	global_load_dwordx4 v[64:67], v[96:97], off offset:256
	v_and_b32_e32 v103, 0xffff0000, v103
	s_waitcnt vmcnt(15)
	v_lshlrev_b32_e32 v140, 16, v106
	v_and_b32_e32 v141, 0xffff0000, v106
	v_lshlrev_b32_e32 v106, 16, v107
	v_and_b32_e32 v107, 0xffff0000, v107
	v_lshlrev_b32_e32 v138, 16, v104
	v_and_b32_e32 v139, 0xffff0000, v104
	v_lshlrev_b32_e32 v104, 16, v105
	v_and_b32_e32 v105, 0xffff0000, v105
	v_pk_fma_f32 v[62:63], v[62:63], v[102:103], v[106:107]
	v_lshlrev_b32_e32 v102, 16, v108
	v_and_b32_e32 v103, 0xffff0000, v108
	v_lshlrev_b32_e32 v106, 16, v109
	v_and_b32_e32 v107, 0xffff0000, v109
	v_pk_fma_f32 v[104:105], v[58:59], v[104:105], v[106:107]
	v_pk_fma_f32 v[58:59], v[56:57], v[138:139], v[102:103]
	v_pk_fma_f32 v[60:61], v[60:61], v[136:137], v[140:141]
	s_andn2_b64 vcc, exec, s[42:43]
	v_cvt_pk_bf16_f32 v56, v60, v61
	v_cvt_pk_bf16_f32 v57, v62, v63
	v_cvt_pk_bf16_f32 v58, v58, v59
	v_cvt_pk_bf16_f32 v59, v104, v105
	global_store_dwordx4 v[134:135], v[56:59], off sc1
	s_mov_b64 s[0:1], -1
	s_waitcnt vmcnt(14)
	v_lshlrev_b32_e32 v60, 16, v112
	v_lshlrev_b32_e32 v56, 16, v110
	v_and_b32_e32 v57, 0xffff0000, v110
	v_lshlrev_b32_e32 v58, 16, v111
	v_and_b32_e32 v59, 0xffff0000, v111
	s_waitcnt vmcnt(13)
	v_lshlrev_b32_e32 v102, 16, v114
	v_and_b32_e32 v103, 0xffff0000, v114
	v_lshlrev_b32_e32 v104, 16, v115
	v_and_b32_e32 v105, 0xffff0000, v115
	v_and_b32_e32 v61, 0xffff0000, v112
	v_lshlrev_b32_e32 v62, 16, v113
	v_and_b32_e32 v63, 0xffff0000, v113
	v_pk_fma_f32 v[54:55], v[54:55], v[58:59], v[104:105]
	v_pk_fma_f32 v[52:53], v[52:53], v[56:57], v[102:103]
	v_lshlrev_b32_e32 v56, 16, v116
	v_and_b32_e32 v57, 0xffff0000, v116
	v_lshlrev_b32_e32 v58, 16, v117
	v_and_b32_e32 v59, 0xffff0000, v117
	v_pk_fma_f32 v[58:59], v[50:51], v[62:63], v[58:59]
	v_pk_fma_f32 v[50:51], v[48:49], v[60:61], v[56:57]
	v_cvt_pk_bf16_f32 v48, v52, v53
	v_cvt_pk_bf16_f32 v49, v54, v55
	s_waitcnt vmcnt(10)
	v_lshlrev_b32_e32 v56, 16, v126
	v_cvt_pk_bf16_f32 v50, v50, v51
	v_cvt_pk_bf16_f32 v51, v58, v59
	global_store_dwordx4 v[134:135], v[48:51], off offset:256 sc1
	v_and_b32_e32 v57, 0xffff0000, v126
	v_lshlrev_b32_e32 v58, 16, v127
	v_lshlrev_b32_e32 v48, 16, v118
	v_and_b32_e32 v49, 0xffff0000, v118
	v_lshlrev_b32_e32 v50, 16, v119
	v_and_b32_e32 v51, 0xffff0000, v119
	v_and_b32_e32 v59, 0xffff0000, v127
	v_lshlrev_b32_e32 v52, 16, v120
	v_and_b32_e32 v53, 0xffff0000, v120
	v_lshlrev_b32_e32 v54, 16, v121
	v_and_b32_e32 v55, 0xffff0000, v121
	v_pk_fma_f32 v[46:47], v[46:47], v[50:51], v[58:59]
	v_pk_fma_f32 v[44:45], v[44:45], v[48:49], v[56:57]
	v_lshlrev_b32_e32 v48, 16, v128
	v_and_b32_e32 v49, 0xffff0000, v128
	v_lshlrev_b32_e32 v50, 16, v129
	v_and_b32_e32 v51, 0xffff0000, v129
	v_pk_fma_f32 v[50:51], v[42:43], v[54:55], v[50:51]
	v_pk_fma_f32 v[42:43], v[40:41], v[52:53], v[48:49]
	v_cvt_pk_bf16_f32 v40, v44, v45
	v_cvt_pk_bf16_f32 v41, v46, v47
	s_waitcnt vmcnt(10)
	v_lshlrev_b32_e32 v48, 16, v130
	v_cvt_pk_bf16_f32 v42, v42, v43
	v_cvt_pk_bf16_f32 v43, v50, v51
	global_store_dwordx4 v[100:101], v[40:43], off sc1
	v_and_b32_e32 v49, 0xffff0000, v130
	v_lshlrev_b32_e32 v50, 16, v131
	v_lshlrev_b32_e32 v40, 16, v122
	v_and_b32_e32 v41, 0xffff0000, v122
	v_lshlrev_b32_e32 v42, 16, v123
	v_and_b32_e32 v43, 0xffff0000, v123
	v_and_b32_e32 v51, 0xffff0000, v131
	v_lshlrev_b32_e32 v44, 16, v124
	v_and_b32_e32 v45, 0xffff0000, v124
	v_lshlrev_b32_e32 v46, 16, v125
	v_and_b32_e32 v47, 0xffff0000, v125
	v_pk_fma_f32 v[38:39], v[38:39], v[42:43], v[50:51]
	v_pk_fma_f32 v[36:37], v[36:37], v[40:41], v[48:49]
	v_lshlrev_b32_e32 v40, 16, v132
	v_and_b32_e32 v41, 0xffff0000, v132
	v_lshlrev_b32_e32 v42, 16, v133
	v_and_b32_e32 v43, 0xffff0000, v133
	v_pk_fma_f32 v[42:43], v[34:35], v[46:47], v[42:43]
	v_pk_fma_f32 v[34:35], v[32:33], v[44:45], v[40:41]
	v_cvt_pk_bf16_f32 v32, v36, v37
	v_cvt_pk_bf16_f32 v33, v38, v39
	s_waitcnt vmcnt(8)
	v_lshlrev_b32_e32 v40, 16, v88
	v_cvt_pk_bf16_f32 v34, v34, v35
	v_cvt_pk_bf16_f32 v35, v42, v43
	global_store_dwordx4 v[100:101], v[32:35], off offset:256 sc1
	v_and_b32_e32 v41, 0xffff0000, v88
	v_lshlrev_b32_e32 v42, 16, v89
	v_lshlrev_b32_e32 v32, 16, v92
	v_and_b32_e32 v33, 0xffff0000, v92
	v_lshlrev_b32_e32 v34, 16, v93
	v_and_b32_e32 v35, 0xffff0000, v93
	v_and_b32_e32 v43, 0xffff0000, v89
	v_lshlrev_b32_e32 v36, 16, v94
	v_and_b32_e32 v37, 0xffff0000, v94
	v_lshlrev_b32_e32 v38, 16, v95
	v_and_b32_e32 v39, 0xffff0000, v95
	v_pk_fma_f32 v[30:31], v[30:31], v[34:35], v[42:43]
	v_pk_fma_f32 v[28:29], v[28:29], v[32:33], v[40:41]
	v_lshlrev_b32_e32 v32, 16, v90
	v_and_b32_e32 v33, 0xffff0000, v90
	v_lshlrev_b32_e32 v34, 16, v91
	v_and_b32_e32 v35, 0xffff0000, v91
	v_pk_fma_f32 v[34:35], v[26:27], v[38:39], v[34:35]
	v_pk_fma_f32 v[26:27], v[24:25], v[36:37], v[32:33]
	v_cvt_pk_bf16_f32 v24, v28, v29
	v_cvt_pk_bf16_f32 v25, v30, v31
	s_waitcnt vmcnt(8)
	v_lshlrev_b32_e32 v32, 16, v80
	v_cvt_pk_bf16_f32 v26, v26, v27
	v_cvt_pk_bf16_f32 v27, v34, v35
	global_store_dwordx4 v[98:99], v[24:27], off sc1
	v_and_b32_e32 v33, 0xffff0000, v80
	v_lshlrev_b32_e32 v34, 16, v81
	v_lshlrev_b32_e32 v24, 16, v84
	v_and_b32_e32 v25, 0xffff0000, v84
	v_lshlrev_b32_e32 v26, 16, v85
	v_and_b32_e32 v27, 0xffff0000, v85
	v_and_b32_e32 v35, 0xffff0000, v81
	v_lshlrev_b32_e32 v28, 16, v86
	v_and_b32_e32 v29, 0xffff0000, v86
	v_lshlrev_b32_e32 v30, 16, v87
	v_and_b32_e32 v31, 0xffff0000, v87
	v_pk_fma_f32 v[22:23], v[22:23], v[26:27], v[34:35]
	v_pk_fma_f32 v[20:21], v[20:21], v[24:25], v[32:33]
	v_lshlrev_b32_e32 v24, 16, v82
	v_and_b32_e32 v25, 0xffff0000, v82
	v_lshlrev_b32_e32 v26, 16, v83
	v_and_b32_e32 v27, 0xffff0000, v83
	v_pk_fma_f32 v[26:27], v[18:19], v[30:31], v[26:27]
	v_pk_fma_f32 v[18:19], v[16:17], v[28:29], v[24:25]
	v_cvt_pk_bf16_f32 v16, v20, v21
	v_cvt_pk_bf16_f32 v17, v22, v23
	s_waitcnt vmcnt(6)
	v_lshlrev_b32_e32 v24, 16, v72
	v_cvt_pk_bf16_f32 v18, v18, v19
	v_cvt_pk_bf16_f32 v19, v26, v27
	global_store_dwordx4 v[98:99], v[16:19], off offset:256 sc1
	v_and_b32_e32 v25, 0xffff0000, v72
	v_lshlrev_b32_e32 v26, 16, v73
	v_lshlrev_b32_e32 v16, 16, v76
	v_and_b32_e32 v17, 0xffff0000, v76
	v_lshlrev_b32_e32 v18, 16, v77
	v_and_b32_e32 v19, 0xffff0000, v77
	v_and_b32_e32 v27, 0xffff0000, v73
	v_lshlrev_b32_e32 v20, 16, v78
	v_and_b32_e32 v21, 0xffff0000, v78
	v_lshlrev_b32_e32 v22, 16, v79
	v_and_b32_e32 v23, 0xffff0000, v79
	v_pk_fma_f32 v[14:15], v[14:15], v[18:19], v[26:27]
	v_pk_fma_f32 v[12:13], v[12:13], v[16:17], v[24:25]
	v_lshlrev_b32_e32 v16, 16, v74
	v_and_b32_e32 v17, 0xffff0000, v74
	v_lshlrev_b32_e32 v18, 16, v75
	v_and_b32_e32 v19, 0xffff0000, v75
	v_pk_fma_f32 v[18:19], v[10:11], v[22:23], v[18:19]
	v_pk_fma_f32 v[10:11], v[8:9], v[20:21], v[16:17]
	v_cvt_pk_bf16_f32 v8, v12, v13
	v_cvt_pk_bf16_f32 v9, v14, v15
	s_waitcnt vmcnt(6)
	v_lshlrev_b32_e32 v16, 16, v64
	v_cvt_pk_bf16_f32 v10, v10, v11
	v_cvt_pk_bf16_f32 v11, v18, v19
	global_store_dwordx4 v[96:97], v[8:11], off sc1
	v_and_b32_e32 v17, 0xffff0000, v64
	v_lshlrev_b32_e32 v18, 16, v65
	v_lshlrev_b32_e32 v8, 16, v68
	v_and_b32_e32 v9, 0xffff0000, v68
	v_lshlrev_b32_e32 v10, 16, v69
	v_and_b32_e32 v11, 0xffff0000, v69
	v_and_b32_e32 v19, 0xffff0000, v65
	v_lshlrev_b32_e32 v12, 16, v70
	v_and_b32_e32 v13, 0xffff0000, v70
	v_lshlrev_b32_e32 v14, 16, v71
	v_and_b32_e32 v15, 0xffff0000, v71
	v_pk_fma_f32 v[6:7], v[6:7], v[10:11], v[18:19]
	v_pk_fma_f32 v[4:5], v[4:5], v[8:9], v[16:17]
	v_lshlrev_b32_e32 v8, 16, v66
	v_and_b32_e32 v9, 0xffff0000, v66
	v_lshlrev_b32_e32 v10, 16, v67
	v_and_b32_e32 v11, 0xffff0000, v67
	v_pk_fma_f32 v[10:11], v[2:3], v[14:15], v[10:11]
	v_pk_fma_f32 v[2:3], v[0:1], v[12:13], v[8:9]
	v_cvt_pk_bf16_f32 v0, v4, v5
	v_cvt_pk_bf16_f32 v1, v6, v7
	s_nop 0
	v_cvt_pk_bf16_f32 v2, v2, v3
	v_cvt_pk_bf16_f32 v3, v10, v11
	global_store_dwordx4 v[96:97], v[0:3], off offset:256 sc1
	s_cbranch_vccnz .LBB0_582
	s_andn2_b64 vcc, exec, s[28:29]
	s_cbranch_vccnz .LBB0_581
	s_barrier
	s_branch .LBB0_581

.LBB0_665:
	s_lshl_b32 s0, s73, 8
	s_add_i32 s0, s0, s67
	v_mbcnt_lo_u32_b32 v128, -1, 0
	v_mbcnt_hi_u32_b32 v128, -1, v128
	s_lshl_b32 s86, s72, 2
	v_and_or_b32 v156, v128, 15, s0
	s_lshl_b32 s0, s72, 8
	v_ashrrev_i32_e32 v129, 1, v128
	s_or_b32 s0, s0, s68
	v_and_b32_e32 v129, -8, v129
	v_add_u32_e32 v154, s0, v129
	v_ashrrev_i32_e32 v155, 31, v154
	v_ashrrev_i32_e32 v157, 31, v156
	v_cmp_gt_u32_e32 vcc, 16, v128
	v_lshl_add_u64 v[158:159], v[154:155], 2, s[46:47]
	v_lshlrev_b64 v[128:129], 12, v[156:157]
	v_lshl_add_u64 v[128:129], v[158:159], 0, v[128:129]
	global_load_dwordx4 v[164:167], v[128:129], off offset:16
	global_load_dwordx4 v[168:171], v[128:129], off
	global_load_dwordx4 v[172:175], v[128:129], off offset:528
	global_load_dwordx4 v[178:181], v[128:129], off offset:512
	v_or_b32_e32 v160, 16, v156
	v_ashrrev_i32_e32 v161, 31, v160
	v_lshlrev_b64 v[128:129], 12, v[160:161]
	v_lshl_add_u64 v[132:133], v[158:159], 0, v[128:129]
	global_load_dwordx4 v[136:139], v[132:133], off offset:16
	global_load_dwordx4 v[140:143], v[132:133], off
	global_load_dwordx4 v[128:131], v[132:133], off offset:528
	s_nop 0
	global_load_dwordx4 v[132:135], v[132:133], off offset:512
	v_lshlrev_b64 v[182:183], 10, v[156:157]
	v_lshl_add_u64 v[182:183], v[182:183], 0, v[154:155]
	s_ashr_i32 s87, s86, 31
	s_waitcnt vmcnt(0)
	v_pk_add_f32 v[122:123], v[122:123], v[166:167]
	v_pk_add_f32 v[126:127], v[126:127], v[170:171]
	v_pk_add_f32 v[124:125], v[124:125], v[168:169]
	v_lshl_add_u64 v[168:169], v[182:183], 2, s[36:37]
	v_pk_add_f32 v[120:121], v[120:121], v[164:165]
	global_store_dwordx4 v[168:169], v[124:127], off sc1
	global_store_dwordx4 v[168:169], v[120:123], off offset:16 sc1
	v_cvt_pk_bf16_f32 v164, v124, v125
	v_cvt_pk_bf16_f32 v165, v126, v127
	v_cvt_pk_bf16_f32 v166, v120, v121
	v_lshl_add_u64 v[170:171], v[182:183], 1, s[48:49]
	v_mul_f32_e32 v125, v125, v125
	v_fmac_f32_e32 v125, v124, v124
	v_mul_f32_e32 v124, v127, v127
	v_fmac_f32_e32 v124, v126, v126
	v_mul_f32_e32 v121, v121, v121
	v_add_f32_e32 v124, v125, v124
	v_fmac_f32_e32 v121, v120, v120
	v_add_f32_e32 v120, v124, v121
	v_mul_f32_e32 v121, v123, v123
	v_fmac_f32_e32 v121, v122, v122
	v_pk_add_f32 v[118:119], v[118:119], v[180:181]
	v_pk_add_f32 v[116:117], v[116:117], v[178:179]
	v_cvt_pk_bf16_f32 v167, v122, v123
	global_store_dwordx4 v[170:171], v[164:167], off sc1
	v_add_f32_e32 v124, v121, v120
	v_pk_add_f32 v[114:115], v[114:115], v[174:175]
	v_pk_add_f32 v[112:113], v[112:113], v[172:173]
	global_store_dwordx4 v[168:169], v[116:119], off offset:512 sc1
	global_store_dwordx4 v[168:169], v[112:115], off offset:528 sc1
	v_cvt_pk_bf16_f32 v120, v116, v117
	v_cvt_pk_bf16_f32 v121, v118, v119
	v_cvt_pk_bf16_f32 v122, v112, v113
	v_cvt_pk_bf16_f32 v123, v114, v115
	s_nop 0
	v_mul_f32_e32 v117, v117, v117
	v_fmac_f32_e32 v117, v116, v116
	v_mul_f32_e32 v116, v119, v119
	v_fmac_f32_e32 v116, v118, v118
	v_mul_f32_e32 v113, v113, v113
	v_add_f32_e32 v116, v117, v116
	v_fmac_f32_e32 v113, v112, v112
	v_add_f32_e32 v112, v116, v113
	v_mul_f32_e32 v113, v115, v115
	v_fmac_f32_e32 v113, v114, v114
	v_add_f32_e32 v112, v113, v112
	v_add_f32_e32 v112, v124, v112
	ds_swizzle_b32 v113, v112 offset:swizzle(SWAP,16)
	global_store_dwordx4 v[170:171], v[120:123], off offset:256 sc1
	s_waitcnt lgkmcnt(0)
	v_add_f32_e32 v112, v112, v113
	v_mov_b32_e32 v113, v112
	v_mov_b32_e32 v114, v112
	s_nop 1
	v_permlane32_swap_b32_e32 v113, v114
	s_and_saveexec_b64 s[0:1], vcc
	s_cbranch_execz .LBB0_667
	v_cmp_eq_u32_e64 s[44:45], v113, v112
	s_lshl_b32 s92, s66, 2
	s_nop 0
	v_cndmask_b32_e64 v113, v113, v114, s[44:45]
	v_add_f32_e32 v114, v112, v113
	v_lshlrev_b64 v[112:113], 6, v[156:157]
	v_lshl_add_u64 v[112:113], s[50:51], 0, v[112:113]
	v_lshl_add_u64 v[112:113], s[86:87], 2, v[112:113]
	v_lshl_add_u64 v[112:113], v[112:113], 0, s[92:93]
	global_store_dword v[112:113], v114, off sc1
.LBB0_667:
	s_or_b64 exec, exec, s[0:1]
	v_lshlrev_b64 v[112:113], 10, v[160:161]
	v_lshl_add_u64 v[116:117], v[112:113], 0, v[154:155]
	v_pk_add_f32 v[110:111], v[110:111], v[142:143]
	v_pk_add_f32 v[108:109], v[108:109], v[140:141]
	v_lshl_add_u64 v[118:119], v[116:117], 2, s[36:37]
	v_pk_add_f32 v[106:107], v[106:107], v[138:139]
	v_pk_add_f32 v[104:105], v[104:105], v[136:137]
	global_store_dwordx4 v[118:119], v[108:111], off sc1
	global_store_dwordx4 v[118:119], v[104:107], off offset:16 sc1
	v_cvt_pk_bf16_f32 v112, v108, v109
	v_cvt_pk_bf16_f32 v113, v110, v111
	v_cvt_pk_bf16_f32 v114, v104, v105
	v_lshl_add_u64 v[116:117], v[116:117], 1, s[48:49]
	v_mul_f32_e32 v109, v109, v109
	v_fmac_f32_e32 v109, v108, v108
	v_mul_f32_e32 v108, v111, v111
	v_fmac_f32_e32 v108, v110, v110
	v_mul_f32_e32 v105, v105, v105
	v_add_f32_e32 v108, v109, v108
	v_fmac_f32_e32 v105, v104, v104
	v_add_f32_e32 v104, v108, v105
	v_mul_f32_e32 v105, v107, v107
	v_fmac_f32_e32 v105, v106, v106
	v_pk_add_f32 v[102:103], v[102:103], v[134:135]
	v_pk_add_f32 v[100:101], v[100:101], v[132:133]
	v_cvt_pk_bf16_f32 v115, v106, v107
	global_store_dwordx4 v[116:117], v[112:115], off sc1
	v_add_f32_e32 v105, v105, v104
	v_pk_add_f32 v[98:99], v[98:99], v[130:131]
	v_pk_add_f32 v[96:97], v[96:97], v[128:129]
	global_store_dwordx4 v[118:119], v[100:103], off offset:512 sc1
	global_store_dwordx4 v[118:119], v[96:99], off offset:528 sc1
	v_cvt_pk_bf16_f32 v104, v100, v101
	s_nop 0
	v_mul_f32_e32 v101, v101, v101
	v_fmac_f32_e32 v101, v100, v100
	v_mul_f32_e32 v100, v103, v103
	v_fmac_f32_e32 v100, v102, v102
	v_add_f32_e32 v100, v101, v100
	v_mul_f32_e32 v101, v97, v97
	v_fmac_f32_e32 v101, v96, v96
	v_add_f32_e32 v100, v100, v101
	v_mul_f32_e32 v101, v99, v99
	v_fmac_f32_e32 v101, v98, v98
	v_add_f32_e32 v100, v101, v100
	v_add_f32_e32 v100, v105, v100
	ds_swizzle_b32 v101, v100 offset:swizzle(SWAP,16)
	v_cvt_pk_bf16_f32 v105, v102, v103
	v_cvt_pk_bf16_f32 v106, v96, v97
	v_cvt_pk_bf16_f32 v107, v98, v99
	global_store_dwordx4 v[116:117], v[104:107], off offset:256 sc1
	s_waitcnt lgkmcnt(0)
	v_add_f32_e32 v96, v100, v101
	v_mov_b32_e32 v97, v96
	v_mov_b32_e32 v98, v96
	s_nop 1
	v_permlane32_swap_b32_e32 v97, v98
	s_and_saveexec_b64 s[0:1], vcc
	s_cbranch_execz .LBB0_669
	v_cmp_eq_u32_e64 s[44:45], v97, v96
	s_lshl_b32 s92, s66, 2
	s_nop 0
	v_cndmask_b32_e64 v97, v97, v98, s[44:45]
	v_add_f32_e32 v98, v96, v97
	v_lshlrev_b64 v[96:97], 6, v[160:161]
	v_lshl_add_u64 v[96:97], s[50:51], 0, v[96:97]
	v_lshl_add_u64 v[96:97], s[86:87], 2, v[96:97]
	v_lshl_add_u64 v[96:97], v[96:97], 0, s[92:93]
	global_store_dword v[96:97], v98, off sc1
.LBB0_669:
	s_or_b64 exec, exec, s[0:1]
	v_or_b32_e32 v114, 32, v156
	v_ashrrev_i32_e32 v115, 31, v114
	v_lshlrev_b64 v[96:97], 12, v[114:115]
	v_lshl_add_u64 v[96:97], v[158:159], 0, v[96:97]
	global_load_dwordx4 v[116:119], v[96:97], off offset:16
	global_load_dwordx4 v[120:123], v[96:97], off
	global_load_dwordx4 v[124:127], v[96:97], off offset:528
	global_load_dwordx4 v[128:131], v[96:97], off offset:512
	v_or_b32_e32 v112, 48, v156
	v_ashrrev_i32_e32 v113, 31, v112
	v_lshlrev_b64 v[96:97], 12, v[112:113]
	v_lshl_add_u64 v[100:101], v[158:159], 0, v[96:97]
	global_load_dwordx4 v[104:107], v[100:101], off offset:16
	global_load_dwordx4 v[108:111], v[100:101], off
	global_load_dwordx4 v[96:99], v[100:101], off offset:528
	s_nop 0
	global_load_dwordx4 v[100:103], v[100:101], off offset:512
	v_lshlrev_b64 v[132:133], 10, v[114:115]
	v_lshl_add_u64 v[132:133], v[132:133], 0, v[154:155]
	s_waitcnt vmcnt(7)
	v_pk_add_f32 v[90:91], v[90:91], v[118:119]
	s_waitcnt vmcnt(6)
	v_pk_add_f32 v[94:95], v[94:95], v[122:123]
	v_pk_add_f32 v[92:93], v[92:93], v[120:121]
	v_lshl_add_u64 v[120:121], v[132:133], 2, s[36:37]
	v_pk_add_f32 v[88:89], v[88:89], v[116:117]
	global_store_dwordx4 v[120:121], v[92:95], off sc1
	global_store_dwordx4 v[120:121], v[88:91], off offset:16 sc1
	v_cvt_pk_bf16_f32 v116, v92, v93
	v_cvt_pk_bf16_f32 v117, v94, v95
	v_cvt_pk_bf16_f32 v118, v88, v89
	v_lshl_add_u64 v[122:123], v[132:133], 1, s[48:49]
	v_mul_f32_e32 v93, v93, v93
	v_fmac_f32_e32 v93, v92, v92
	v_mul_f32_e32 v92, v95, v95
	v_fmac_f32_e32 v92, v94, v94
	v_mul_f32_e32 v89, v89, v89
	v_add_f32_e32 v92, v93, v92
	v_fmac_f32_e32 v89, v88, v88
	v_add_f32_e32 v88, v92, v89
	v_mul_f32_e32 v89, v91, v91
	v_fmac_f32_e32 v89, v90, v90
	s_waitcnt vmcnt(6)
	v_pk_add_f32 v[86:87], v[86:87], v[130:131]
	v_pk_add_f32 v[84:85], v[84:85], v[128:129]
	v_cvt_pk_bf16_f32 v119, v90, v91
	global_store_dwordx4 v[122:123], v[116:119], off sc1
	v_add_f32_e32 v92, v89, v88
	v_pk_add_f32 v[82:83], v[82:83], v[126:127]
	v_pk_add_f32 v[80:81], v[80:81], v[124:125]
	global_store_dwordx4 v[120:121], v[84:87], off offset:512 sc1
	global_store_dwordx4 v[120:121], v[80:83], off offset:528 sc1
	v_cvt_pk_bf16_f32 v88, v84, v85
	v_cvt_pk_bf16_f32 v89, v86, v87
	v_cvt_pk_bf16_f32 v90, v80, v81
	v_cvt_pk_bf16_f32 v91, v82, v83
	s_nop 0
	v_mul_f32_e32 v85, v85, v85
	v_fmac_f32_e32 v85, v84, v84
	v_mul_f32_e32 v84, v87, v87
	v_fmac_f32_e32 v84, v86, v86
	v_mul_f32_e32 v81, v81, v81
	v_add_f32_e32 v84, v85, v84
	v_fmac_f32_e32 v81, v80, v80
	v_add_f32_e32 v80, v84, v81
	v_mul_f32_e32 v81, v83, v83
	v_fmac_f32_e32 v81, v82, v82
	v_add_f32_e32 v80, v81, v80
	v_add_f32_e32 v80, v92, v80
	ds_swizzle_b32 v81, v80 offset:swizzle(SWAP,16)
	global_store_dwordx4 v[122:123], v[88:91], off offset:256 sc1
	s_waitcnt lgkmcnt(0)
	v_add_f32_e32 v80, v80, v81
	v_mov_b32_e32 v81, v80
	v_mov_b32_e32 v82, v80
	s_nop 1
	v_permlane32_swap_b32_e32 v81, v82
	s_and_saveexec_b64 s[0:1], vcc
	s_cbranch_execz .LBB0_671
	v_cmp_eq_u32_e64 s[44:45], v81, v80
	s_lshl_b32 s92, s66, 2
	s_nop 0
	v_cndmask_b32_e64 v81, v81, v82, s[44:45]
	v_add_f32_e32 v82, v80, v81
	v_lshlrev_b64 v[80:81], 6, v[114:115]
	v_lshl_add_u64 v[80:81], s[50:51], 0, v[80:81]
	v_lshl_add_u64 v[80:81], s[86:87], 2, v[80:81]
	v_lshl_add_u64 v[80:81], v[80:81], 0, s[92:93]
	global_store_dword v[80:81], v82, off sc1
.LBB0_671:
	s_or_b64 exec, exec, s[0:1]
	v_lshlrev_b64 v[80:81], 10, v[112:113]
	v_lshl_add_u64 v[84:85], v[80:81], 0, v[154:155]
	s_waitcnt vmcnt(8)
	v_pk_add_f32 v[78:79], v[78:79], v[110:111]
	v_pk_add_f32 v[76:77], v[76:77], v[108:109]
	v_lshl_add_u64 v[86:87], v[84:85], 2, s[36:37]
	v_pk_add_f32 v[74:75], v[74:75], v[106:107]
	v_pk_add_f32 v[72:73], v[72:73], v[104:105]
	global_store_dwordx4 v[86:87], v[76:79], off sc1
	global_store_dwordx4 v[86:87], v[72:75], off offset:16 sc1
	v_cvt_pk_bf16_f32 v80, v76, v77
	v_cvt_pk_bf16_f32 v81, v78, v79
	v_cvt_pk_bf16_f32 v82, v72, v73
	v_lshl_add_u64 v[84:85], v[84:85], 1, s[48:49]
	v_mul_f32_e32 v77, v77, v77
	v_fmac_f32_e32 v77, v76, v76
	v_mul_f32_e32 v76, v79, v79
	v_fmac_f32_e32 v76, v78, v78
	v_mul_f32_e32 v73, v73, v73
	v_add_f32_e32 v76, v77, v76
	v_fmac_f32_e32 v73, v72, v72
	v_add_f32_e32 v72, v76, v73
	v_mul_f32_e32 v73, v75, v75
	v_fmac_f32_e32 v73, v74, v74
	s_waitcnt vmcnt(8)
	v_pk_add_f32 v[70:71], v[70:71], v[102:103]
	v_pk_add_f32 v[68:69], v[68:69], v[100:101]
	v_cvt_pk_bf16_f32 v83, v74, v75
	global_store_dwordx4 v[84:85], v[80:83], off sc1
	v_add_f32_e32 v73, v73, v72
	v_pk_add_f32 v[66:67], v[66:67], v[98:99]
	v_pk_add_f32 v[64:65], v[64:65], v[96:97]
	global_store_dwordx4 v[86:87], v[68:71], off offset:512 sc1
	global_store_dwordx4 v[86:87], v[64:67], off offset:528 sc1
	v_cvt_pk_bf16_f32 v72, v68, v69
	s_nop 0
	v_mul_f32_e32 v69, v69, v69
	v_fmac_f32_e32 v69, v68, v68
	v_mul_f32_e32 v68, v71, v71
	v_fmac_f32_e32 v68, v70, v70
	v_add_f32_e32 v68, v69, v68
	v_mul_f32_e32 v69, v65, v65
	v_fmac_f32_e32 v69, v64, v64
	v_add_f32_e32 v68, v68, v69
	v_mul_f32_e32 v69, v67, v67
	v_fmac_f32_e32 v69, v66, v66
	v_add_f32_e32 v68, v69, v68
	v_add_f32_e32 v68, v73, v68
	ds_swizzle_b32 v69, v68 offset:swizzle(SWAP,16)
	v_cvt_pk_bf16_f32 v73, v70, v71
	v_cvt_pk_bf16_f32 v74, v64, v65
	v_cvt_pk_bf16_f32 v75, v66, v67
	global_store_dwordx4 v[84:85], v[72:75], off offset:256 sc1
	s_waitcnt lgkmcnt(0)
	v_add_f32_e32 v64, v68, v69
	v_mov_b32_e32 v65, v64
	v_mov_b32_e32 v66, v64
	s_nop 1
	v_permlane32_swap_b32_e32 v65, v66
	s_and_saveexec_b64 s[0:1], vcc
	s_cbranch_execz .LBB0_673
	v_cmp_eq_u32_e64 s[44:45], v65, v64
	s_lshl_b32 s92, s66, 2
	s_nop 0
	v_cndmask_b32_e64 v65, v65, v66, s[44:45]
	v_add_f32_e32 v66, v64, v65
	v_lshlrev_b64 v[64:65], 6, v[112:113]
	v_lshl_add_u64 v[64:65], s[50:51], 0, v[64:65]
	v_lshl_add_u64 v[64:65], s[86:87], 2, v[64:65]
	v_lshl_add_u64 v[64:65], v[64:65], 0, s[92:93]
	global_store_dword v[64:65], v66, off sc1
.LBB0_673:
	s_or_b64 exec, exec, s[0:1]
	v_add_u32_e32 v82, 0x80, v156
	v_ashrrev_i32_e32 v83, 31, v82
	v_lshlrev_b64 v[64:65], 12, v[82:83]
	v_lshl_add_u64 v[64:65], v[158:159], 0, v[64:65]
	global_load_dwordx4 v[84:87], v[64:65], off offset:16
	global_load_dwordx4 v[88:91], v[64:65], off
	global_load_dwordx4 v[92:95], v[64:65], off offset:528
	global_load_dwordx4 v[96:99], v[64:65], off offset:512
	v_add_u32_e32 v80, 0x90, v156
	v_ashrrev_i32_e32 v81, 31, v80
	v_lshlrev_b64 v[64:65], 12, v[80:81]
	v_lshl_add_u64 v[68:69], v[158:159], 0, v[64:65]
	global_load_dwordx4 v[72:75], v[68:69], off offset:16
	global_load_dwordx4 v[76:79], v[68:69], off
	global_load_dwordx4 v[64:67], v[68:69], off offset:528
	s_nop 0
	global_load_dwordx4 v[68:71], v[68:69], off offset:512
	v_lshlrev_b64 v[100:101], 10, v[82:83]
	v_lshl_add_u64 v[100:101], v[100:101], 0, v[154:155]
	s_waitcnt vmcnt(7)
	v_pk_add_f32 v[58:59], v[58:59], v[86:87]
	s_waitcnt vmcnt(6)
	v_pk_add_f32 v[62:63], v[62:63], v[90:91]
	v_pk_add_f32 v[60:61], v[60:61], v[88:89]
	v_lshl_add_u64 v[88:89], v[100:101], 2, s[36:37]
	v_pk_add_f32 v[56:57], v[56:57], v[84:85]
	global_store_dwordx4 v[88:89], v[60:63], off sc1
	global_store_dwordx4 v[88:89], v[56:59], off offset:16 sc1
	v_cvt_pk_bf16_f32 v84, v60, v61
	v_cvt_pk_bf16_f32 v85, v62, v63
	v_cvt_pk_bf16_f32 v86, v56, v57
	v_lshl_add_u64 v[90:91], v[100:101], 1, s[48:49]
	v_mul_f32_e32 v61, v61, v61
	v_fmac_f32_e32 v61, v60, v60
	v_mul_f32_e32 v60, v63, v63
	v_fmac_f32_e32 v60, v62, v62
	v_mul_f32_e32 v57, v57, v57
	v_add_f32_e32 v60, v61, v60
	v_fmac_f32_e32 v57, v56, v56
	v_add_f32_e32 v56, v60, v57
	v_mul_f32_e32 v57, v59, v59
	v_fmac_f32_e32 v57, v58, v58
	s_waitcnt vmcnt(6)
	v_pk_add_f32 v[54:55], v[54:55], v[98:99]
	v_pk_add_f32 v[52:53], v[52:53], v[96:97]
	v_cvt_pk_bf16_f32 v87, v58, v59
	global_store_dwordx4 v[90:91], v[84:87], off sc1
	v_add_f32_e32 v60, v57, v56
	v_pk_add_f32 v[50:51], v[50:51], v[94:95]
	v_pk_add_f32 v[48:49], v[48:49], v[92:93]
	global_store_dwordx4 v[88:89], v[52:55], off offset:512 sc1
	global_store_dwordx4 v[88:89], v[48:51], off offset:528 sc1
	v_cvt_pk_bf16_f32 v56, v52, v53
	v_cvt_pk_bf16_f32 v57, v54, v55
	v_cvt_pk_bf16_f32 v58, v48, v49
	v_cvt_pk_bf16_f32 v59, v50, v51
	s_nop 0
	v_mul_f32_e32 v53, v53, v53
	v_fmac_f32_e32 v53, v52, v52
	v_mul_f32_e32 v52, v55, v55
	v_fmac_f32_e32 v52, v54, v54
	v_mul_f32_e32 v49, v49, v49
	v_add_f32_e32 v52, v53, v52
	v_fmac_f32_e32 v49, v48, v48
	v_add_f32_e32 v48, v52, v49
	v_mul_f32_e32 v49, v51, v51
	v_fmac_f32_e32 v49, v50, v50
	v_add_f32_e32 v48, v49, v48
	v_add_f32_e32 v48, v60, v48
	ds_swizzle_b32 v49, v48 offset:swizzle(SWAP,16)
	global_store_dwordx4 v[90:91], v[56:59], off offset:256 sc1
	s_waitcnt lgkmcnt(0)
	v_add_f32_e32 v48, v48, v49
	v_mov_b32_e32 v49, v48
	v_mov_b32_e32 v50, v48
	s_nop 1
	v_permlane32_swap_b32_e32 v49, v50
	s_and_saveexec_b64 s[0:1], vcc
	s_cbranch_execz .LBB0_675
	v_cmp_eq_u32_e64 s[44:45], v49, v48
	s_lshl_b32 s92, s66, 2
	s_nop 0
	v_cndmask_b32_e64 v49, v49, v50, s[44:45]
	v_add_f32_e32 v50, v48, v49
	v_lshlrev_b64 v[48:49], 6, v[82:83]
	v_lshl_add_u64 v[48:49], s[50:51], 0, v[48:49]
	v_lshl_add_u64 v[48:49], s[86:87], 2, v[48:49]
	v_lshl_add_u64 v[48:49], v[48:49], 0, s[92:93]
	global_store_dword v[48:49], v50, off sc1
.LBB0_675:
	s_or_b64 exec, exec, s[0:1]
	v_lshlrev_b64 v[48:49], 10, v[80:81]
	v_lshl_add_u64 v[52:53], v[48:49], 0, v[154:155]
	s_waitcnt vmcnt(8)
	v_pk_add_f32 v[46:47], v[46:47], v[78:79]
	v_pk_add_f32 v[44:45], v[44:45], v[76:77]
	v_lshl_add_u64 v[54:55], v[52:53], 2, s[36:37]
	v_pk_add_f32 v[42:43], v[42:43], v[74:75]
	v_pk_add_f32 v[40:41], v[40:41], v[72:73]
	global_store_dwordx4 v[54:55], v[44:47], off sc1
	global_store_dwordx4 v[54:55], v[40:43], off offset:16 sc1
	v_cvt_pk_bf16_f32 v48, v44, v45
	v_cvt_pk_bf16_f32 v49, v46, v47
	v_cvt_pk_bf16_f32 v50, v40, v41
	v_lshl_add_u64 v[52:53], v[52:53], 1, s[48:49]
	v_mul_f32_e32 v45, v45, v45
	v_fmac_f32_e32 v45, v44, v44
	v_mul_f32_e32 v44, v47, v47
	v_fmac_f32_e32 v44, v46, v46
	v_mul_f32_e32 v41, v41, v41
	v_add_f32_e32 v44, v45, v44
	v_fmac_f32_e32 v41, v40, v40
	v_add_f32_e32 v40, v44, v41
	v_mul_f32_e32 v41, v43, v43
	v_fmac_f32_e32 v41, v42, v42
	s_waitcnt vmcnt(8)
	v_pk_add_f32 v[38:39], v[38:39], v[70:71]
	v_pk_add_f32 v[36:37], v[36:37], v[68:69]
	v_cvt_pk_bf16_f32 v51, v42, v43
	global_store_dwordx4 v[52:53], v[48:51], off sc1
	v_add_f32_e32 v41, v41, v40
	v_pk_add_f32 v[34:35], v[34:35], v[66:67]
	v_pk_add_f32 v[32:33], v[32:33], v[64:65]
	global_store_dwordx4 v[54:55], v[36:39], off offset:512 sc1
	global_store_dwordx4 v[54:55], v[32:35], off offset:528 sc1
	v_cvt_pk_bf16_f32 v40, v36, v37
	s_nop 0
	v_mul_f32_e32 v37, v37, v37
	v_fmac_f32_e32 v37, v36, v36
	v_mul_f32_e32 v36, v39, v39
	v_fmac_f32_e32 v36, v38, v38
	v_add_f32_e32 v36, v37, v36
	v_mul_f32_e32 v37, v33, v33
	v_fmac_f32_e32 v37, v32, v32
	v_add_f32_e32 v36, v36, v37
	v_mul_f32_e32 v37, v35, v35
	v_fmac_f32_e32 v37, v34, v34
	v_add_f32_e32 v36, v37, v36
	v_add_f32_e32 v36, v41, v36
	ds_swizzle_b32 v37, v36 offset:swizzle(SWAP,16)
	v_cvt_pk_bf16_f32 v41, v38, v39
	v_cvt_pk_bf16_f32 v42, v32, v33
	v_cvt_pk_bf16_f32 v43, v34, v35
	global_store_dwordx4 v[52:53], v[40:43], off offset:256 sc1
	s_waitcnt lgkmcnt(0)
	v_add_f32_e32 v32, v36, v37
	v_mov_b32_e32 v33, v32
	v_mov_b32_e32 v34, v32
	s_nop 1
	v_permlane32_swap_b32_e32 v33, v34
	s_and_saveexec_b64 s[0:1], vcc
	s_cbranch_execz .LBB0_677
	v_cmp_eq_u32_e64 s[44:45], v33, v32
	s_lshl_b32 s92, s66, 2
	s_nop 0
	v_cndmask_b32_e64 v33, v33, v34, s[44:45]
	v_add_f32_e32 v34, v32, v33
	v_lshlrev_b64 v[32:33], 6, v[80:81]
	v_lshl_add_u64 v[32:33], s[50:51], 0, v[32:33]
	v_lshl_add_u64 v[32:33], s[86:87], 2, v[32:33]
	v_lshl_add_u64 v[32:33], v[32:33], 0, s[92:93]
	global_store_dword v[32:33], v34, off sc1
.LBB0_677:
	s_or_b64 exec, exec, s[0:1]
	v_add_u32_e32 v50, 0xa0, v156
	v_ashrrev_i32_e32 v51, 31, v50
	v_lshlrev_b64 v[32:33], 12, v[50:51]
	v_lshl_add_u64 v[32:33], v[158:159], 0, v[32:33]
	global_load_dwordx4 v[52:55], v[32:33], off offset:16
	global_load_dwordx4 v[56:59], v[32:33], off
	global_load_dwordx4 v[60:63], v[32:33], off offset:528
	global_load_dwordx4 v[64:67], v[32:33], off offset:512
	v_add_u32_e32 v48, 0xb0, v156
	v_ashrrev_i32_e32 v49, 31, v48
	v_lshlrev_b64 v[32:33], 12, v[48:49]
	v_lshl_add_u64 v[36:37], v[158:159], 0, v[32:33]
	global_load_dwordx4 v[40:43], v[36:37], off offset:16
	global_load_dwordx4 v[44:47], v[36:37], off
	global_load_dwordx4 v[32:35], v[36:37], off offset:528
	s_nop 0
	global_load_dwordx4 v[36:39], v[36:37], off offset:512
	v_lshlrev_b64 v[68:69], 10, v[50:51]
	v_lshl_add_u64 v[68:69], v[68:69], 0, v[154:155]
	s_waitcnt vmcnt(7)
	v_pk_add_f32 v[26:27], v[26:27], v[54:55]
	s_waitcnt vmcnt(6)
	v_pk_add_f32 v[30:31], v[30:31], v[58:59]
	v_pk_add_f32 v[28:29], v[28:29], v[56:57]
	v_lshl_add_u64 v[56:57], v[68:69], 2, s[36:37]
	v_pk_add_f32 v[24:25], v[24:25], v[52:53]
	global_store_dwordx4 v[56:57], v[28:31], off sc1
	global_store_dwordx4 v[56:57], v[24:27], off offset:16 sc1
	v_cvt_pk_bf16_f32 v52, v28, v29
	v_cvt_pk_bf16_f32 v53, v30, v31
	v_cvt_pk_bf16_f32 v54, v24, v25
	v_lshl_add_u64 v[58:59], v[68:69], 1, s[48:49]
	v_mul_f32_e32 v29, v29, v29
	v_fmac_f32_e32 v29, v28, v28
	v_mul_f32_e32 v28, v31, v31
	v_fmac_f32_e32 v28, v30, v30
	v_mul_f32_e32 v25, v25, v25
	v_add_f32_e32 v28, v29, v28
	v_fmac_f32_e32 v25, v24, v24
	v_add_f32_e32 v24, v28, v25
	v_mul_f32_e32 v25, v27, v27
	v_fmac_f32_e32 v25, v26, v26
	s_waitcnt vmcnt(6)
	v_pk_add_f32 v[22:23], v[22:23], v[66:67]
	v_pk_add_f32 v[20:21], v[20:21], v[64:65]
	v_cvt_pk_bf16_f32 v55, v26, v27
	global_store_dwordx4 v[58:59], v[52:55], off sc1
	v_add_f32_e32 v28, v25, v24
	v_pk_add_f32 v[18:19], v[18:19], v[62:63]
	v_pk_add_f32 v[16:17], v[16:17], v[60:61]
	global_store_dwordx4 v[56:57], v[20:23], off offset:512 sc1
	global_store_dwordx4 v[56:57], v[16:19], off offset:528 sc1
	v_cvt_pk_bf16_f32 v24, v20, v21
	v_cvt_pk_bf16_f32 v25, v22, v23
	v_cvt_pk_bf16_f32 v26, v16, v17
	v_cvt_pk_bf16_f32 v27, v18, v19
	s_nop 0
	v_mul_f32_e32 v21, v21, v21
	v_fmac_f32_e32 v21, v20, v20
	v_mul_f32_e32 v20, v23, v23
	v_fmac_f32_e32 v20, v22, v22
	v_mul_f32_e32 v17, v17, v17
	v_add_f32_e32 v20, v21, v20
	v_fmac_f32_e32 v17, v16, v16
	v_add_f32_e32 v16, v20, v17
	v_mul_f32_e32 v17, v19, v19
	v_fmac_f32_e32 v17, v18, v18
	v_add_f32_e32 v16, v17, v16
	v_add_f32_e32 v16, v28, v16
	ds_swizzle_b32 v17, v16 offset:swizzle(SWAP,16)
	global_store_dwordx4 v[58:59], v[24:27], off offset:256 sc1
	s_waitcnt lgkmcnt(0)
	v_add_f32_e32 v16, v16, v17
	v_mov_b32_e32 v17, v16
	v_mov_b32_e32 v18, v16
	s_nop 1
	v_permlane32_swap_b32_e32 v17, v18
	s_and_saveexec_b64 s[0:1], vcc
	s_cbranch_execz .LBB0_679
	v_cmp_eq_u32_e64 s[44:45], v17, v16
	s_lshl_b32 s92, s66, 2
	s_nop 0
	v_cndmask_b32_e64 v17, v17, v18, s[44:45]
	v_add_f32_e32 v18, v16, v17
	v_lshlrev_b64 v[16:17], 6, v[50:51]
	v_lshl_add_u64 v[16:17], s[50:51], 0, v[16:17]
	v_lshl_add_u64 v[16:17], s[86:87], 2, v[16:17]
	v_lshl_add_u64 v[16:17], v[16:17], 0, s[92:93]
	global_store_dword v[16:17], v18, off sc1
.LBB0_679:
	s_or_b64 exec, exec, s[0:1]
	v_lshlrev_b64 v[16:17], 10, v[48:49]
	v_lshl_add_u64 v[20:21], v[16:17], 0, v[154:155]
	s_waitcnt vmcnt(8)
	v_pk_add_f32 v[14:15], v[14:15], v[46:47]
	v_pk_add_f32 v[12:13], v[12:13], v[44:45]
	v_lshl_add_u64 v[22:23], v[20:21], 2, s[36:37]
	v_pk_add_f32 v[10:11], v[10:11], v[42:43]
	v_pk_add_f32 v[8:9], v[8:9], v[40:41]
	global_store_dwordx4 v[22:23], v[12:15], off sc1
	global_store_dwordx4 v[22:23], v[8:11], off offset:16 sc1
	v_cvt_pk_bf16_f32 v16, v12, v13
	v_cvt_pk_bf16_f32 v17, v14, v15
	v_cvt_pk_bf16_f32 v18, v8, v9
	v_lshl_add_u64 v[20:21], v[20:21], 1, s[48:49]
	v_mul_f32_e32 v13, v13, v13
	v_fmac_f32_e32 v13, v12, v12
	v_mul_f32_e32 v12, v15, v15
	v_fmac_f32_e32 v12, v14, v14
	v_mul_f32_e32 v9, v9, v9
	v_add_f32_e32 v12, v13, v12
	v_fmac_f32_e32 v9, v8, v8
	v_add_f32_e32 v8, v12, v9
	v_mul_f32_e32 v9, v11, v11
	v_fmac_f32_e32 v9, v10, v10
	s_waitcnt vmcnt(8)
	v_pk_add_f32 v[6:7], v[6:7], v[38:39]
	v_pk_add_f32 v[4:5], v[4:5], v[36:37]
	v_cvt_pk_bf16_f32 v19, v10, v11
	global_store_dwordx4 v[20:21], v[16:19], off sc1
	v_add_f32_e32 v9, v9, v8
	v_pk_add_f32 v[2:3], v[2:3], v[34:35]
	v_pk_add_f32 v[0:1], v[0:1], v[32:33]
	global_store_dwordx4 v[22:23], v[4:7], off offset:512 sc1
	global_store_dwordx4 v[22:23], v[0:3], off offset:528 sc1
	v_cvt_pk_bf16_f32 v8, v4, v5
	s_nop 0
	v_mul_f32_e32 v5, v5, v5
	v_fmac_f32_e32 v5, v4, v4
	v_mul_f32_e32 v4, v7, v7
	v_fmac_f32_e32 v4, v6, v6
	v_add_f32_e32 v4, v5, v4
	v_mul_f32_e32 v5, v1, v1
	v_fmac_f32_e32 v5, v0, v0
	v_add_f32_e32 v4, v4, v5
	v_mul_f32_e32 v5, v3, v3
	v_fmac_f32_e32 v5, v2, v2
	v_add_f32_e32 v4, v5, v4
	v_add_f32_e32 v4, v9, v4
	ds_swizzle_b32 v5, v4 offset:swizzle(SWAP,16)
	v_cvt_pk_bf16_f32 v9, v6, v7
	v_cvt_pk_bf16_f32 v10, v0, v1
	v_cvt_pk_bf16_f32 v11, v2, v3
	global_store_dwordx4 v[20:21], v[8:11], off offset:256 sc1
	s_waitcnt lgkmcnt(0)
	v_add_f32_e32 v0, v4, v5
	v_mov_b32_e32 v1, v0
	v_mov_b32_e32 v2, v0
	s_nop 1
	v_permlane32_swap_b32_e32 v1, v2
	s_and_saveexec_b64 s[0:1], vcc
	s_cbranch_execz .LBB0_681
	v_cmp_eq_u32_e32 vcc, v1, v0
	s_lshl_b32 s92, s66, 2
	s_nop 0
	v_cndmask_b32_e32 v1, v1, v2, vcc
	v_add_f32_e32 v2, v0, v1
	v_lshlrev_b64 v[0:1], 6, v[48:49]
	v_lshl_add_u64 v[0:1], s[50:51], 0, v[0:1]
	v_lshl_add_u64 v[0:1], s[86:87], 2, v[0:1]
	v_lshl_add_u64 v[0:1], v[0:1], 0, s[92:93]
	global_store_dword v[0:1], v2, off sc1

.LBB0_933:
	s_lshl_b32 s0, s68, 8
	s_add_i32 s0, s0, s60
	v_mbcnt_lo_u32_b32 v182, -1, 0
	v_mbcnt_hi_u32_b32 v182, -1, v182
	s_lshl_b32 s54, s67, 2
	v_and_or_b32 v156, v182, 15, s0
	s_lshl_b32 s0, s67, 8
	v_ashrrev_i32_e32 v128, 1, v182
	s_or_b32 s0, s0, s61
	v_and_b32_e32 v128, -8, v128
	v_add_u32_e32 v154, s0, v128
	v_ashrrev_i32_e32 v155, 31, v154
	v_ashrrev_i32_e32 v157, 31, v156
	v_lshl_add_u64 v[158:159], v[154:155], 2, s[30:31]
	v_lshlrev_b64 v[128:129], 12, v[156:157]
	v_lshl_add_u64 v[174:175], v[158:159], 0, v[128:129]
	global_load_dwordx4 v[166:169], v[174:175], off
	global_load_dwordx4 v[170:173], v[174:175], off offset:16
	global_load_dwordx4 v[178:181], v[174:175], off offset:512
	global_load_dwordx4 v[186:189], v[174:175], off offset:528
	v_or_b32_e32 v160, 16, v156
	v_ashrrev_i32_e32 v161, 31, v160
	v_lshlrev_b64 v[128:129], 12, v[160:161]
	v_lshl_add_u64 v[162:163], v[158:159], 0, v[128:129]
	global_load_dwordx4 v[136:139], v[162:163], off offset:16
	global_load_dwordx4 v[140:143], v[162:163], off
	global_load_dwordx4 v[128:131], v[162:163], off offset:528
	global_load_dwordx4 v[132:135], v[162:163], off offset:512
	v_cmp_gt_u32_e32 vcc, 16, v182
	v_lshlrev_b64 v[182:183], 10, v[156:157]
	v_lshl_add_u64 v[182:183], v[182:183], 0, v[154:155]
	v_lshl_add_u64 v[182:183], v[182:183], 1, s[38:39]
	s_ashr_i32 s55, s54, 31
	s_waitcnt vmcnt(0)
	v_pk_add_f32 v[126:127], v[126:127], v[168:169]
	v_pk_add_f32 v[124:125], v[124:125], v[166:167]
	v_pk_add_f32 v[118:119], v[118:119], v[180:181]
	v_pk_add_f32 v[116:117], v[116:117], v[178:179]
	v_pk_add_f32 v[122:123], v[122:123], v[172:173]
	v_pk_add_f32 v[120:121], v[120:121], v[170:171]
	v_pk_add_f32 v[112:113], v[112:113], v[186:187]
	global_store_dwordx4 v[174:175], v[124:127], off sc1
	global_store_dwordx4 v[174:175], v[120:123], off offset:16 sc1
	v_cvt_pk_bf16_f32 v166, v124, v125
	v_cvt_pk_bf16_f32 v167, v126, v127
	v_mul_f32_e32 v170, v117, v117
	v_mul_f32_e32 v125, v125, v125
	v_mul_f32_e32 v127, v127, v127
	v_mul_f32_e32 v171, v119, v119
	v_pk_add_f32 v[114:115], v[114:115], v[188:189]
	v_cvt_pk_bf16_f32 v168, v120, v121
	v_mul_f32_e32 v121, v121, v121
	v_mul_f32_e32 v172, v113, v113
	v_fmac_f32_e32 v125, v124, v124
	v_fmac_f32_e32 v127, v126, v126
	v_fmac_f32_e32 v170, v116, v116
	v_fmac_f32_e32 v171, v118, v118
	v_cvt_pk_bf16_f32 v169, v122, v123
	v_mul_f32_e32 v123, v123, v123
	v_mul_f32_e32 v173, v115, v115
	global_store_dwordx4 v[182:183], v[166:169], off sc1
	v_fmac_f32_e32 v121, v120, v120
	global_store_dwordx4 v[174:175], v[116:119], off offset:512 sc1
	global_store_dwordx4 v[174:175], v[112:115], off offset:528 sc1
	v_cvt_pk_bf16_f32 v120, v116, v117
	v_fmac_f32_e32 v172, v112, v112
	v_add_f32_e32 v116, v125, v127
	v_add_f32_e32 v117, v170, v171
	v_fmac_f32_e32 v123, v122, v122
	v_fmac_f32_e32 v173, v114, v114
	v_add_f32_e32 v116, v116, v121
	v_add_f32_e32 v117, v117, v172
	v_add_f32_e32 v116, v123, v116
	v_add_f32_e32 v117, v173, v117
	v_add_f32_e32 v116, v116, v117
	ds_swizzle_b32 v117, v116 offset:swizzle(SWAP,16)
	v_cvt_pk_bf16_f32 v121, v118, v119
	v_cvt_pk_bf16_f32 v122, v112, v113
	v_cvt_pk_bf16_f32 v123, v114, v115
	global_store_dwordx4 v[182:183], v[120:123], off offset:256 sc1
	s_waitcnt lgkmcnt(0)
	v_add_f32_e32 v112, v116, v117
	v_mov_b32_e32 v113, v112
	v_mov_b32_e32 v114, v112
	s_nop 1
	v_permlane32_swap_b32_e32 v113, v114
	s_and_saveexec_b64 s[0:1], vcc
	s_cbranch_execz .LBB0_935
	v_cmp_eq_u32_e64 s[42:43], v113, v112
	s_lshl_b32 s92, s57, 2
	s_nop 0
	v_cndmask_b32_e64 v113, v113, v114, s[42:43]
	v_add_f32_e32 v114, v112, v113
	v_lshlrev_b64 v[112:113], 6, v[156:157]
	v_lshl_add_u64 v[112:113], s[44:45], 0, v[112:113]
	v_lshl_add_u64 v[112:113], s[54:55], 2, v[112:113]
	v_lshl_add_u64 v[112:113], v[112:113], 0, s[92:93]
	global_store_dword v[112:113], v114, off sc1
.LBB0_935:
	s_or_b64 exec, exec, s[0:1]
	v_lshlrev_b64 v[112:113], 10, v[160:161]
	v_pk_add_f32 v[110:111], v[110:111], v[142:143]
	v_pk_add_f32 v[108:109], v[108:109], v[140:141]
	v_lshl_add_u64 v[116:117], v[112:113], 0, v[154:155]
	v_pk_add_f32 v[106:107], v[106:107], v[138:139]
	v_pk_add_f32 v[104:105], v[104:105], v[136:137]
	global_store_dwordx4 v[162:163], v[108:111], off sc1
	global_store_dwordx4 v[162:163], v[104:107], off offset:16 sc1
	v_cvt_pk_bf16_f32 v112, v108, v109
	v_cvt_pk_bf16_f32 v113, v110, v111
	v_cvt_pk_bf16_f32 v114, v104, v105
	v_lshl_add_u64 v[116:117], v[116:117], 1, s[38:39]
	v_mul_f32_e32 v109, v109, v109
	v_fmac_f32_e32 v109, v108, v108
	v_mul_f32_e32 v108, v111, v111
	v_fmac_f32_e32 v108, v110, v110
	v_mul_f32_e32 v105, v105, v105
	v_add_f32_e32 v108, v109, v108
	v_fmac_f32_e32 v105, v104, v104
	v_add_f32_e32 v104, v108, v105
	v_mul_f32_e32 v105, v107, v107
	v_fmac_f32_e32 v105, v106, v106
	v_pk_add_f32 v[102:103], v[102:103], v[134:135]
	v_pk_add_f32 v[100:101], v[100:101], v[132:133]
	v_cvt_pk_bf16_f32 v115, v106, v107
	global_store_dwordx4 v[116:117], v[112:115], off sc1
	v_add_f32_e32 v105, v105, v104
	v_pk_add_f32 v[98:99], v[98:99], v[130:131]
	v_pk_add_f32 v[96:97], v[96:97], v[128:129]
	global_store_dwordx4 v[162:163], v[100:103], off offset:512 sc1
	global_store_dwordx4 v[162:163], v[96:99], off offset:528 sc1
	v_cvt_pk_bf16_f32 v104, v100, v101
	s_nop 0
	v_mul_f32_e32 v101, v101, v101
	v_fmac_f32_e32 v101, v100, v100
	v_mul_f32_e32 v100, v103, v103
	v_fmac_f32_e32 v100, v102, v102
	v_add_f32_e32 v100, v101, v100
	v_mul_f32_e32 v101, v97, v97
	v_fmac_f32_e32 v101, v96, v96
	v_add_f32_e32 v100, v100, v101
	v_mul_f32_e32 v101, v99, v99
	v_fmac_f32_e32 v101, v98, v98
	v_add_f32_e32 v100, v101, v100
	v_add_f32_e32 v100, v105, v100
	ds_swizzle_b32 v101, v100 offset:swizzle(SWAP,16)
	v_cvt_pk_bf16_f32 v105, v102, v103
	v_cvt_pk_bf16_f32 v106, v96, v97
	v_cvt_pk_bf16_f32 v107, v98, v99
	global_store_dwordx4 v[116:117], v[104:107], off offset:256 sc1
	s_waitcnt lgkmcnt(0)
	v_add_f32_e32 v96, v100, v101
	v_mov_b32_e32 v97, v96
	v_mov_b32_e32 v98, v96
	s_nop 1
	v_permlane32_swap_b32_e32 v97, v98
	s_and_saveexec_b64 s[0:1], vcc
	s_cbranch_execz .LBB0_937
	v_cmp_eq_u32_e64 s[42:43], v97, v96
	s_lshl_b32 s92, s57, 2
	s_nop 0
	v_cndmask_b32_e64 v97, v97, v98, s[42:43]
	v_add_f32_e32 v98, v96, v97
	v_lshlrev_b64 v[96:97], 6, v[160:161]
	v_lshl_add_u64 v[96:97], s[44:45], 0, v[96:97]
	v_lshl_add_u64 v[96:97], s[54:55], 2, v[96:97]
	v_lshl_add_u64 v[96:97], v[96:97], 0, s[92:93]
	global_store_dword v[96:97], v98, off sc1
.LBB0_937:
	s_or_b64 exec, exec, s[0:1]
	v_or_b32_e32 v116, 32, v156
	v_ashrrev_i32_e32 v117, 31, v116
	v_lshlrev_b64 v[96:97], 12, v[116:117]
	v_lshl_add_u64 v[134:135], v[158:159], 0, v[96:97]
	global_load_dwordx4 v[118:121], v[134:135], off
	global_load_dwordx4 v[122:125], v[134:135], off offset:16
	global_load_dwordx4 v[126:129], v[134:135], off offset:512
	global_load_dwordx4 v[130:133], v[134:135], off offset:528
	v_or_b32_e32 v112, 48, v156
	v_ashrrev_i32_e32 v113, 31, v112
	v_lshlrev_b64 v[96:97], 12, v[112:113]
	v_lshl_add_u64 v[114:115], v[158:159], 0, v[96:97]
	global_load_dwordx4 v[104:107], v[114:115], off offset:16
	global_load_dwordx4 v[108:111], v[114:115], off
	global_load_dwordx4 v[96:99], v[114:115], off offset:528
	global_load_dwordx4 v[100:103], v[114:115], off offset:512
	v_lshlrev_b64 v[136:137], 10, v[116:117]
	v_lshl_add_u64 v[136:137], v[136:137], 0, v[154:155]
	v_lshl_add_u64 v[136:137], v[136:137], 1, s[38:39]
	s_waitcnt vmcnt(7)
	v_pk_add_f32 v[94:95], v[94:95], v[120:121]
	v_pk_add_f32 v[92:93], v[92:93], v[118:119]
	s_waitcnt vmcnt(5)
	v_pk_add_f32 v[86:87], v[86:87], v[128:129]
	v_pk_add_f32 v[84:85], v[84:85], v[126:127]
	v_pk_add_f32 v[90:91], v[90:91], v[124:125]
	v_pk_add_f32 v[88:89], v[88:89], v[122:123]
	s_waitcnt vmcnt(4)
	v_pk_add_f32 v[80:81], v[80:81], v[130:131]
	global_store_dwordx4 v[134:135], v[92:95], off sc1
	global_store_dwordx4 v[134:135], v[88:91], off offset:16 sc1
	v_cvt_pk_bf16_f32 v118, v92, v93
	v_cvt_pk_bf16_f32 v119, v94, v95
	v_mul_f32_e32 v122, v85, v85
	v_mul_f32_e32 v93, v93, v93
	v_mul_f32_e32 v95, v95, v95
	v_mul_f32_e32 v123, v87, v87
	v_pk_add_f32 v[82:83], v[82:83], v[132:133]
	v_cvt_pk_bf16_f32 v120, v88, v89
	v_mul_f32_e32 v89, v89, v89
	v_mul_f32_e32 v124, v81, v81
	v_fmac_f32_e32 v93, v92, v92
	v_fmac_f32_e32 v95, v94, v94
	v_fmac_f32_e32 v122, v84, v84
	v_fmac_f32_e32 v123, v86, v86
	v_cvt_pk_bf16_f32 v121, v90, v91
	v_mul_f32_e32 v91, v91, v91
	v_mul_f32_e32 v125, v83, v83
	global_store_dwordx4 v[136:137], v[118:121], off sc1
	v_fmac_f32_e32 v89, v88, v88
	global_store_dwordx4 v[134:135], v[84:87], off offset:512 sc1
	global_store_dwordx4 v[134:135], v[80:83], off offset:528 sc1
	v_cvt_pk_bf16_f32 v88, v84, v85
	v_fmac_f32_e32 v124, v80, v80
	v_add_f32_e32 v84, v93, v95
	v_add_f32_e32 v85, v122, v123
	v_fmac_f32_e32 v91, v90, v90
	v_fmac_f32_e32 v125, v82, v82
	v_add_f32_e32 v84, v84, v89
	v_add_f32_e32 v85, v85, v124
	v_add_f32_e32 v84, v91, v84
	v_add_f32_e32 v85, v125, v85
	v_add_f32_e32 v84, v84, v85
	ds_swizzle_b32 v85, v84 offset:swizzle(SWAP,16)
	v_cvt_pk_bf16_f32 v89, v86, v87
	v_cvt_pk_bf16_f32 v90, v80, v81
	v_cvt_pk_bf16_f32 v91, v82, v83
	global_store_dwordx4 v[136:137], v[88:91], off offset:256 sc1
	s_waitcnt lgkmcnt(0)
	v_add_f32_e32 v80, v84, v85
	v_mov_b32_e32 v81, v80
	v_mov_b32_e32 v82, v80
	s_nop 1
	v_permlane32_swap_b32_e32 v81, v82
	s_and_saveexec_b64 s[0:1], vcc
	s_cbranch_execz .LBB0_939
	v_cmp_eq_u32_e64 s[42:43], v81, v80
	s_lshl_b32 s92, s57, 2
	s_nop 0
	v_cndmask_b32_e64 v81, v81, v82, s[42:43]
	v_add_f32_e32 v82, v80, v81
	v_lshlrev_b64 v[80:81], 6, v[116:117]
	v_lshl_add_u64 v[80:81], s[44:45], 0, v[80:81]
	v_lshl_add_u64 v[80:81], s[54:55], 2, v[80:81]
	v_lshl_add_u64 v[80:81], v[80:81], 0, s[92:93]
	global_store_dword v[80:81], v82, off sc1
.LBB0_939:
	s_or_b64 exec, exec, s[0:1]
	v_lshlrev_b64 v[80:81], 10, v[112:113]
	s_waitcnt vmcnt(8)
	v_pk_add_f32 v[78:79], v[78:79], v[110:111]
	v_pk_add_f32 v[76:77], v[76:77], v[108:109]
	v_lshl_add_u64 v[84:85], v[80:81], 0, v[154:155]
	v_pk_add_f32 v[74:75], v[74:75], v[106:107]
	v_pk_add_f32 v[72:73], v[72:73], v[104:105]
	global_store_dwordx4 v[114:115], v[76:79], off sc1
	global_store_dwordx4 v[114:115], v[72:75], off offset:16 sc1
	v_cvt_pk_bf16_f32 v80, v76, v77
	v_cvt_pk_bf16_f32 v81, v78, v79
	v_cvt_pk_bf16_f32 v82, v72, v73
	v_lshl_add_u64 v[84:85], v[84:85], 1, s[38:39]
	v_mul_f32_e32 v77, v77, v77
	v_fmac_f32_e32 v77, v76, v76
	v_mul_f32_e32 v76, v79, v79
	v_fmac_f32_e32 v76, v78, v78
	v_mul_f32_e32 v73, v73, v73
	v_add_f32_e32 v76, v77, v76
	v_fmac_f32_e32 v73, v72, v72
	v_add_f32_e32 v72, v76, v73
	v_mul_f32_e32 v73, v75, v75
	v_fmac_f32_e32 v73, v74, v74
	s_waitcnt vmcnt(8)
	v_pk_add_f32 v[70:71], v[70:71], v[102:103]
	v_pk_add_f32 v[68:69], v[68:69], v[100:101]
	v_cvt_pk_bf16_f32 v83, v74, v75
	global_store_dwordx4 v[84:85], v[80:83], off sc1
	v_add_f32_e32 v73, v73, v72
	v_pk_add_f32 v[66:67], v[66:67], v[98:99]
	v_pk_add_f32 v[64:65], v[64:65], v[96:97]
	global_store_dwordx4 v[114:115], v[68:71], off offset:512 sc1
	global_store_dwordx4 v[114:115], v[64:67], off offset:528 sc1
	v_cvt_pk_bf16_f32 v72, v68, v69
	s_nop 0
	v_mul_f32_e32 v69, v69, v69
	v_fmac_f32_e32 v69, v68, v68
	v_mul_f32_e32 v68, v71, v71
	v_fmac_f32_e32 v68, v70, v70
	v_add_f32_e32 v68, v69, v68
	v_mul_f32_e32 v69, v65, v65
	v_fmac_f32_e32 v69, v64, v64
	v_add_f32_e32 v68, v68, v69
	v_mul_f32_e32 v69, v67, v67
	v_fmac_f32_e32 v69, v66, v66
	v_add_f32_e32 v68, v69, v68
	v_add_f32_e32 v68, v73, v68
	ds_swizzle_b32 v69, v68 offset:swizzle(SWAP,16)
	v_cvt_pk_bf16_f32 v73, v70, v71
	v_cvt_pk_bf16_f32 v74, v64, v65
	v_cvt_pk_bf16_f32 v75, v66, v67
	global_store_dwordx4 v[84:85], v[72:75], off offset:256 sc1
	s_waitcnt lgkmcnt(0)
	v_add_f32_e32 v64, v68, v69
	v_mov_b32_e32 v65, v64
	v_mov_b32_e32 v66, v64
	s_nop 1
	v_permlane32_swap_b32_e32 v65, v66
	s_and_saveexec_b64 s[0:1], vcc
	s_cbranch_execz .LBB0_941
	v_cmp_eq_u32_e64 s[42:43], v65, v64
	s_lshl_b32 s92, s57, 2
	s_nop 0
	v_cndmask_b32_e64 v65, v65, v66, s[42:43]
	v_add_f32_e32 v66, v64, v65
	v_lshlrev_b64 v[64:65], 6, v[112:113]
	v_lshl_add_u64 v[64:65], s[44:45], 0, v[64:65]
	v_lshl_add_u64 v[64:65], s[54:55], 2, v[64:65]
	v_lshl_add_u64 v[64:65], v[64:65], 0, s[92:93]
	global_store_dword v[64:65], v66, off sc1
.LBB0_941:
	s_or_b64 exec, exec, s[0:1]
	v_add_u32_e32 v84, 0x80, v156
	v_ashrrev_i32_e32 v85, 31, v84
	v_lshlrev_b64 v[64:65], 12, v[84:85]
	v_lshl_add_u64 v[102:103], v[158:159], 0, v[64:65]
	global_load_dwordx4 v[86:89], v[102:103], off
	global_load_dwordx4 v[90:93], v[102:103], off offset:16
	global_load_dwordx4 v[94:97], v[102:103], off offset:512
	global_load_dwordx4 v[98:101], v[102:103], off offset:528
	v_add_u32_e32 v80, 0x90, v156
	v_ashrrev_i32_e32 v81, 31, v80
	v_lshlrev_b64 v[64:65], 12, v[80:81]
	v_lshl_add_u64 v[82:83], v[158:159], 0, v[64:65]
	global_load_dwordx4 v[72:75], v[82:83], off offset:16
	global_load_dwordx4 v[76:79], v[82:83], off
	global_load_dwordx4 v[64:67], v[82:83], off offset:528
	global_load_dwordx4 v[68:71], v[82:83], off offset:512
	v_lshlrev_b64 v[104:105], 10, v[84:85]
	v_lshl_add_u64 v[104:105], v[104:105], 0, v[154:155]
	v_lshl_add_u64 v[104:105], v[104:105], 1, s[38:39]
	s_waitcnt vmcnt(7)
	v_pk_add_f32 v[62:63], v[62:63], v[88:89]
	v_pk_add_f32 v[60:61], v[60:61], v[86:87]
	s_waitcnt vmcnt(5)
	v_pk_add_f32 v[54:55], v[54:55], v[96:97]
	v_pk_add_f32 v[52:53], v[52:53], v[94:95]
	v_pk_add_f32 v[58:59], v[58:59], v[92:93]
	v_pk_add_f32 v[56:57], v[56:57], v[90:91]
	s_waitcnt vmcnt(4)
	v_pk_add_f32 v[48:49], v[48:49], v[98:99]
	global_store_dwordx4 v[102:103], v[60:63], off sc1
	global_store_dwordx4 v[102:103], v[56:59], off offset:16 sc1
	v_cvt_pk_bf16_f32 v86, v60, v61
	v_cvt_pk_bf16_f32 v87, v62, v63
	v_mul_f32_e32 v90, v53, v53
	v_mul_f32_e32 v61, v61, v61
	v_mul_f32_e32 v63, v63, v63
	v_mul_f32_e32 v91, v55, v55
	v_pk_add_f32 v[50:51], v[50:51], v[100:101]
	v_cvt_pk_bf16_f32 v88, v56, v57
	v_mul_f32_e32 v57, v57, v57
	v_mul_f32_e32 v92, v49, v49
	v_fmac_f32_e32 v61, v60, v60
	v_fmac_f32_e32 v63, v62, v62
	v_fmac_f32_e32 v90, v52, v52
	v_fmac_f32_e32 v91, v54, v54
	v_cvt_pk_bf16_f32 v89, v58, v59
	v_mul_f32_e32 v59, v59, v59
	v_mul_f32_e32 v93, v51, v51
	global_store_dwordx4 v[104:105], v[86:89], off sc1
	v_fmac_f32_e32 v57, v56, v56
	global_store_dwordx4 v[102:103], v[52:55], off offset:512 sc1
	global_store_dwordx4 v[102:103], v[48:51], off offset:528 sc1
	v_cvt_pk_bf16_f32 v56, v52, v53
	v_fmac_f32_e32 v92, v48, v48
	v_add_f32_e32 v52, v61, v63
	v_add_f32_e32 v53, v90, v91
	v_fmac_f32_e32 v59, v58, v58
	v_fmac_f32_e32 v93, v50, v50
	v_add_f32_e32 v52, v52, v57
	v_add_f32_e32 v53, v53, v92
	v_add_f32_e32 v52, v59, v52
	v_add_f32_e32 v53, v93, v53
	v_add_f32_e32 v52, v52, v53
	ds_swizzle_b32 v53, v52 offset:swizzle(SWAP,16)
	v_cvt_pk_bf16_f32 v57, v54, v55
	v_cvt_pk_bf16_f32 v58, v48, v49
	v_cvt_pk_bf16_f32 v59, v50, v51
	global_store_dwordx4 v[104:105], v[56:59], off offset:256 sc1
	s_waitcnt lgkmcnt(0)
	v_add_f32_e32 v48, v52, v53
	v_mov_b32_e32 v49, v48
	v_mov_b32_e32 v50, v48
	s_nop 1
	v_permlane32_swap_b32_e32 v49, v50
	s_and_saveexec_b64 s[0:1], vcc
	s_cbranch_execz .LBB0_943
	v_cmp_eq_u32_e64 s[42:43], v49, v48
	s_lshl_b32 s92, s57, 2
	s_nop 0
	v_cndmask_b32_e64 v49, v49, v50, s[42:43]
	v_add_f32_e32 v50, v48, v49
	v_lshlrev_b64 v[48:49], 6, v[84:85]
	v_lshl_add_u64 v[48:49], s[44:45], 0, v[48:49]
	v_lshl_add_u64 v[48:49], s[54:55], 2, v[48:49]
	v_lshl_add_u64 v[48:49], v[48:49], 0, s[92:93]
	global_store_dword v[48:49], v50, off sc1
.LBB0_943:
	s_or_b64 exec, exec, s[0:1]
	v_lshlrev_b64 v[48:49], 10, v[80:81]
	s_waitcnt vmcnt(8)
	v_pk_add_f32 v[46:47], v[46:47], v[78:79]
	v_pk_add_f32 v[44:45], v[44:45], v[76:77]
	v_lshl_add_u64 v[52:53], v[48:49], 0, v[154:155]
	v_pk_add_f32 v[42:43], v[42:43], v[74:75]
	v_pk_add_f32 v[40:41], v[40:41], v[72:73]
	global_store_dwordx4 v[82:83], v[44:47], off sc1
	global_store_dwordx4 v[82:83], v[40:43], off offset:16 sc1
	v_cvt_pk_bf16_f32 v48, v44, v45
	v_cvt_pk_bf16_f32 v49, v46, v47
	v_cvt_pk_bf16_f32 v50, v40, v41
	v_lshl_add_u64 v[52:53], v[52:53], 1, s[38:39]
	v_mul_f32_e32 v45, v45, v45
	v_fmac_f32_e32 v45, v44, v44
	v_mul_f32_e32 v44, v47, v47
	v_fmac_f32_e32 v44, v46, v46
	v_mul_f32_e32 v41, v41, v41
	v_add_f32_e32 v44, v45, v44
	v_fmac_f32_e32 v41, v40, v40
	v_add_f32_e32 v40, v44, v41
	v_mul_f32_e32 v41, v43, v43
	v_fmac_f32_e32 v41, v42, v42
	s_waitcnt vmcnt(8)
	v_pk_add_f32 v[38:39], v[38:39], v[70:71]
	v_pk_add_f32 v[36:37], v[36:37], v[68:69]
	v_cvt_pk_bf16_f32 v51, v42, v43
	global_store_dwordx4 v[52:53], v[48:51], off sc1
	v_add_f32_e32 v41, v41, v40
	v_pk_add_f32 v[34:35], v[34:35], v[66:67]
	v_pk_add_f32 v[32:33], v[32:33], v[64:65]
	global_store_dwordx4 v[82:83], v[36:39], off offset:512 sc1
	global_store_dwordx4 v[82:83], v[32:35], off offset:528 sc1
	v_cvt_pk_bf16_f32 v40, v36, v37
	s_nop 0
	v_mul_f32_e32 v37, v37, v37
	v_fmac_f32_e32 v37, v36, v36
	v_mul_f32_e32 v36, v39, v39
	v_fmac_f32_e32 v36, v38, v38
	v_add_f32_e32 v36, v37, v36
	v_mul_f32_e32 v37, v33, v33
	v_fmac_f32_e32 v37, v32, v32
	v_add_f32_e32 v36, v36, v37
	v_mul_f32_e32 v37, v35, v35
	v_fmac_f32_e32 v37, v34, v34
	v_add_f32_e32 v36, v37, v36
	v_add_f32_e32 v36, v41, v36
	ds_swizzle_b32 v37, v36 offset:swizzle(SWAP,16)
	v_cvt_pk_bf16_f32 v41, v38, v39
	v_cvt_pk_bf16_f32 v42, v32, v33
	v_cvt_pk_bf16_f32 v43, v34, v35
	global_store_dwordx4 v[52:53], v[40:43], off offset:256 sc1
	s_waitcnt lgkmcnt(0)
	v_add_f32_e32 v32, v36, v37
	v_mov_b32_e32 v33, v32
	v_mov_b32_e32 v34, v32
	s_nop 1
	v_permlane32_swap_b32_e32 v33, v34
	s_and_saveexec_b64 s[0:1], vcc
	s_cbranch_execz .LBB0_945
	v_cmp_eq_u32_e64 s[42:43], v33, v32
	s_lshl_b32 s92, s57, 2
	s_nop 0
	v_cndmask_b32_e64 v33, v33, v34, s[42:43]
	v_add_f32_e32 v34, v32, v33
	v_lshlrev_b64 v[32:33], 6, v[80:81]
	v_lshl_add_u64 v[32:33], s[44:45], 0, v[32:33]
	v_lshl_add_u64 v[32:33], s[54:55], 2, v[32:33]
	v_lshl_add_u64 v[32:33], v[32:33], 0, s[92:93]
	global_store_dword v[32:33], v34, off sc1
.LBB0_945:
	s_or_b64 exec, exec, s[0:1]
	v_add_u32_e32 v52, 0xa0, v156
	v_ashrrev_i32_e32 v53, 31, v52
	v_lshlrev_b64 v[32:33], 12, v[52:53]
	v_lshl_add_u64 v[70:71], v[158:159], 0, v[32:33]
	global_load_dwordx4 v[54:57], v[70:71], off
	global_load_dwordx4 v[58:61], v[70:71], off offset:16
	global_load_dwordx4 v[62:65], v[70:71], off offset:512
	global_load_dwordx4 v[66:69], v[70:71], off offset:528
	v_add_u32_e32 v48, 0xb0, v156
	v_ashrrev_i32_e32 v49, 31, v48
	v_lshlrev_b64 v[32:33], 12, v[48:49]
	v_lshl_add_u64 v[50:51], v[158:159], 0, v[32:33]
	global_load_dwordx4 v[40:43], v[50:51], off offset:16
	global_load_dwordx4 v[44:47], v[50:51], off
	global_load_dwordx4 v[32:35], v[50:51], off offset:528
	global_load_dwordx4 v[36:39], v[50:51], off offset:512
	v_lshlrev_b64 v[72:73], 10, v[52:53]
	v_lshl_add_u64 v[72:73], v[72:73], 0, v[154:155]
	v_lshl_add_u64 v[72:73], v[72:73], 1, s[38:39]
	s_waitcnt vmcnt(7)
	v_pk_add_f32 v[30:31], v[30:31], v[56:57]
	v_pk_add_f32 v[28:29], v[28:29], v[54:55]
	s_waitcnt vmcnt(5)
	v_pk_add_f32 v[22:23], v[22:23], v[64:65]
	v_pk_add_f32 v[20:21], v[20:21], v[62:63]
	v_pk_add_f32 v[26:27], v[26:27], v[60:61]
	v_pk_add_f32 v[24:25], v[24:25], v[58:59]
	s_waitcnt vmcnt(4)
	v_pk_add_f32 v[16:17], v[16:17], v[66:67]
	global_store_dwordx4 v[70:71], v[28:31], off sc1
	global_store_dwordx4 v[70:71], v[24:27], off offset:16 sc1
	v_cvt_pk_bf16_f32 v54, v28, v29
	v_cvt_pk_bf16_f32 v55, v30, v31
	v_mul_f32_e32 v58, v21, v21
	v_mul_f32_e32 v29, v29, v29
	v_mul_f32_e32 v31, v31, v31
	v_mul_f32_e32 v59, v23, v23
	v_pk_add_f32 v[18:19], v[18:19], v[68:69]
	v_cvt_pk_bf16_f32 v56, v24, v25
	v_mul_f32_e32 v25, v25, v25
	v_mul_f32_e32 v60, v17, v17
	v_fmac_f32_e32 v29, v28, v28
	v_fmac_f32_e32 v31, v30, v30
	v_fmac_f32_e32 v58, v20, v20
	v_fmac_f32_e32 v59, v22, v22
	v_cvt_pk_bf16_f32 v57, v26, v27
	v_mul_f32_e32 v27, v27, v27
	v_mul_f32_e32 v61, v19, v19
	global_store_dwordx4 v[72:73], v[54:57], off sc1
	v_fmac_f32_e32 v25, v24, v24
	global_store_dwordx4 v[70:71], v[20:23], off offset:512 sc1
	global_store_dwordx4 v[70:71], v[16:19], off offset:528 sc1
	v_cvt_pk_bf16_f32 v24, v20, v21
	v_fmac_f32_e32 v60, v16, v16
	v_add_f32_e32 v20, v29, v31
	v_add_f32_e32 v21, v58, v59
	v_fmac_f32_e32 v27, v26, v26
	v_fmac_f32_e32 v61, v18, v18
	v_add_f32_e32 v20, v20, v25
	v_add_f32_e32 v21, v21, v60
	v_add_f32_e32 v20, v27, v20
	v_add_f32_e32 v21, v61, v21
	v_add_f32_e32 v20, v20, v21
	ds_swizzle_b32 v21, v20 offset:swizzle(SWAP,16)
	v_cvt_pk_bf16_f32 v25, v22, v23
	v_cvt_pk_bf16_f32 v26, v16, v17
	v_cvt_pk_bf16_f32 v27, v18, v19
	global_store_dwordx4 v[72:73], v[24:27], off offset:256 sc1
	s_waitcnt lgkmcnt(0)
	v_add_f32_e32 v16, v20, v21
	v_mov_b32_e32 v17, v16
	v_mov_b32_e32 v18, v16
	s_nop 1
	v_permlane32_swap_b32_e32 v17, v18
	s_and_saveexec_b64 s[0:1], vcc
	s_cbranch_execz .LBB0_947
	v_cmp_eq_u32_e64 s[42:43], v17, v16
	s_lshl_b32 s92, s57, 2
	s_nop 0
	v_cndmask_b32_e64 v17, v17, v18, s[42:43]
	v_add_f32_e32 v18, v16, v17
	v_lshlrev_b64 v[16:17], 6, v[52:53]
	v_lshl_add_u64 v[16:17], s[44:45], 0, v[16:17]
	v_lshl_add_u64 v[16:17], s[54:55], 2, v[16:17]
	v_lshl_add_u64 v[16:17], v[16:17], 0, s[92:93]
	global_store_dword v[16:17], v18, off sc1
.LBB0_947:
	s_or_b64 exec, exec, s[0:1]
	v_lshlrev_b64 v[16:17], 10, v[48:49]
	s_waitcnt vmcnt(8)
	v_pk_add_f32 v[14:15], v[14:15], v[46:47]
	v_pk_add_f32 v[12:13], v[12:13], v[44:45]
	v_lshl_add_u64 v[20:21], v[16:17], 0, v[154:155]
	v_pk_add_f32 v[10:11], v[10:11], v[42:43]
	v_pk_add_f32 v[8:9], v[8:9], v[40:41]
	global_store_dwordx4 v[50:51], v[12:15], off sc1
	global_store_dwordx4 v[50:51], v[8:11], off offset:16 sc1
	v_cvt_pk_bf16_f32 v16, v12, v13
	v_cvt_pk_bf16_f32 v17, v14, v15
	v_cvt_pk_bf16_f32 v18, v8, v9
	v_lshl_add_u64 v[20:21], v[20:21], 1, s[38:39]
	v_mul_f32_e32 v13, v13, v13
	v_fmac_f32_e32 v13, v12, v12
	v_mul_f32_e32 v12, v15, v15
	v_fmac_f32_e32 v12, v14, v14
	v_mul_f32_e32 v9, v9, v9
	v_add_f32_e32 v12, v13, v12
	v_fmac_f32_e32 v9, v8, v8
	v_add_f32_e32 v8, v12, v9
	v_mul_f32_e32 v9, v11, v11
	v_fmac_f32_e32 v9, v10, v10
	s_waitcnt vmcnt(8)
	v_pk_add_f32 v[6:7], v[6:7], v[38:39]
	v_pk_add_f32 v[4:5], v[4:5], v[36:37]
	v_cvt_pk_bf16_f32 v19, v10, v11
	global_store_dwordx4 v[20:21], v[16:19], off sc1
	v_add_f32_e32 v9, v9, v8
	v_pk_add_f32 v[2:3], v[2:3], v[34:35]
	v_pk_add_f32 v[0:1], v[0:1], v[32:33]
	global_store_dwordx4 v[50:51], v[4:7], off offset:512 sc1
	global_store_dwordx4 v[50:51], v[0:3], off offset:528 sc1
	v_cvt_pk_bf16_f32 v8, v4, v5
	s_nop 0
	v_mul_f32_e32 v5, v5, v5
	v_fmac_f32_e32 v5, v4, v4
	v_mul_f32_e32 v4, v7, v7
	v_fmac_f32_e32 v4, v6, v6
	v_add_f32_e32 v4, v5, v4
	v_mul_f32_e32 v5, v1, v1
	v_fmac_f32_e32 v5, v0, v0
	v_add_f32_e32 v4, v4, v5
	v_mul_f32_e32 v5, v3, v3
	v_fmac_f32_e32 v5, v2, v2
	v_add_f32_e32 v4, v5, v4
	v_add_f32_e32 v4, v9, v4
	ds_swizzle_b32 v5, v4 offset:swizzle(SWAP,16)
	v_cvt_pk_bf16_f32 v9, v6, v7
	v_cvt_pk_bf16_f32 v10, v0, v1
	v_cvt_pk_bf16_f32 v11, v2, v3
	global_store_dwordx4 v[20:21], v[8:11], off offset:256 sc1
	s_waitcnt lgkmcnt(0)
	v_add_f32_e32 v0, v4, v5
	v_mov_b32_e32 v1, v0
	v_mov_b32_e32 v2, v0
	s_nop 1
	v_permlane32_swap_b32_e32 v1, v2
	s_and_saveexec_b64 s[0:1], vcc
	s_cbranch_execz .LBB0_949
	v_cmp_eq_u32_e32 vcc, v1, v0
	s_lshl_b32 s92, s57, 2
	s_nop 0
	v_cndmask_b32_e32 v1, v1, v2, vcc
	v_add_f32_e32 v2, v0, v1
	v_lshlrev_b64 v[0:1], 6, v[48:49]
	v_lshl_add_u64 v[0:1], s[44:45], 0, v[0:1]
	v_lshl_add_u64 v[0:1], s[54:55], 2, v[0:1]
	v_lshl_add_u64 v[0:1], v[0:1], 0, s[92:93]
	global_store_dword v[0:1], v2, off sc1
